# GEMM epilogues (GU, in-proj): issue sw-vector loads together with ss row loads instead of after the first wait
# speedup vs baseline: 1.0269x; 1.0057x over previous
; #define PG8_STAGE(bufoff, gbase, voff) do { _Pragma("unroll") for (int _i = 0; _i < 2; ++_i) \
;         __builtin_amdgcn_global_load_lds((const unsigned*)((const char*)(gbase) + (voff)[_i]), (LAS unsigned*)(lds + (bufoff) + ldsw + _i * 8192), 16, 0, 0); } while (0)
; #define PG8_LDA(dst, b, h) do { _Pragma("unroll") for (int m = 0; m < 4; ++m) _Pragma("unroll") for (int k = 0; k < 2; ++k) dst[m][k] = *(const LAS bf16x8*)(lds + PG8_SA(b, h) + aoff + m * 2048 + k * 1024); } while (0)
; #define PG8_LDB(dst, b, h) do { _Pragma("unroll") for (int n = 0; n < 2; ++n) _Pragma("unroll") for (int k = 0; k < 2; ++k) dst[n][k] = *(const LAS bf16x8*)(lds + PG8_SB(b, h) + boff + n * 2048 + k * 1024); } while (0)
; #define PG8_WAIT_V(n) asm volatile("s_waitcnt vmcnt(" #n ")" ::: "memory")
; #define PG8_WAIT_L(n) asm volatile("s_waitcnt lgkmcnt(" #n ")" ::: "memory")
; #define PG8_BAR __builtin_amdgcn_s_barrier()
; #define PG8_SCHED __builtin_amdgcn_sched_barrier(0)
; template <class Epi>
; __device__ __forceinline__ void gemm_phase(LAS unsigned char* lds, const Gemm g, const StaticOrder& S, const Epi& E) {
;     ...
;         for (int t = 0; t < nt; t += 2) {
;             const bool last = (t == nt - 2);
;             const char* a1 = cA + (size_t)(t + 1) * kstep;
;             const char* a2 = last ? nA : cA + (size_t)(t + 2) * kstep; const char* b2 = last ? nB : cB + (size_t)(t + 2) * kstep;
;             const char* a3 = a2 + kstep; const char* b3 = b2 + kstep;
;             PG8_LDB(B0, 0, 0); PG8_SCHED; PG8_LDA(At, 0, 0); PG8_STAGE(PG8_SA(1, 1), a1 + hstep, voffA);
;             PG8_WAIT_L(8); PG8_BAR; PG8_WAIT_L(0); PG8_MMA(0, 0, At, B0); PG8_BAR; PG8_SCHED;
;             PG8_LDB(B1, 0, 1); PG8_STAGE(PG8_SB(0, 0), b2, voffB);
;             PG8_BAR; PG8_WAIT_L(0); PG8_MMA(0, 1, At, B1); PG8_BAR;
;             PG8_LDA(At, 0, 1); PG8_STAGE(PG8_SA(0, 0), a2, voffA);
;             PG8_BAR; PG8_WAIT_L(0); PG8_MMA(1, 0, At, B0); PG8_BAR; PG8_SCHED;
;             PG8_STAGE(PG8_SB(0, 1), b2 + hstep, voffB);
;             PG8_WAIT_V(6); PG8_BAR; PG8_MMA(1, 1, At, B1); PG8_BAR;
;             PG8_LDB(B0, 1, 0); PG8_SCHED; PG8_LDA(At, 1, 0); PG8_STAGE(PG8_SA(0, 1), a2 + hstep, voffA);
;             PG8_WAIT_L(8); PG8_BAR; PG8_WAIT_L(0); PG8_MMA(0, 0, At, B0); PG8_BAR; PG8_SCHED;
.LBB0_2079:
	s_add_u32 s0, s22, 0xfffc0080
	s_addc_u32 s1, s23, -1
	s_add_i32 s62, 0, 0x10000
	v_add_u32_e32 v142, s62, v161
	ds_read_b128 v[122:125], v142
	ds_read_b128 v[126:129], v142 offset:1024
	ds_read_b128 v[138:141], v142 offset:2048
	ds_read_b128 v[142:145], v142 offset:3072
	s_cmp_eq_u32 s61, 12
	s_cselect_b32 s27, s15, s1
	s_cselect_b32 s26, s57, s0
	s_cselect_b32 s25, s13, s60
	s_cselect_b32 s24, s58, s59
	v_lshl_add_u64 v[186:187], s[22:23], 0, v[152:153]
	s_add_i32 m0, s21, 0xc000
	ds_read_b128 v[166:169], v165
	ds_read_b128 v[170:173], v165 offset:1024
	ds_read_b128 v[174:177], v165 offset:2048
	ds_read_b128 v[190:193], v165 offset:3072
	ds_read_b128 v[194:197], v165 offset:4096
	ds_read_b128 v[198:201], v165 offset:5120
	ds_read_b128 v[202:205], v165 offset:6144
	ds_read_b128 v[206:209], v165 offset:7168
	global_load_lds_dwordx4 v[186:187], off
	v_lshl_add_u64 v[186:187], s[22:23], 0, v[154:155]
	s_add_i32 m0, s21, 0xe000
	s_nop 0
	global_load_lds_dwordx4 v[186:187], off
	s_waitcnt lgkmcnt(8)
	s_barrier
	s_waitcnt lgkmcnt(0)
	s_setprio 1
	s_waitcnt lgkmcnt(0)
	v_mfma_f32_16x16x32_bf16 v[134:137], v[122:125], v[166:169], v[134:137]
	v_mfma_f32_16x16x32_bf16 v[130:133], v[138:141], v[166:169], v[130:133]
	v_mfma_f32_16x16x32_bf16 v[118:121], v[122:125], v[174:177], v[118:121]
	v_mfma_f32_16x16x32_bf16 v[114:117], v[138:141], v[174:177], v[114:117]
	v_mfma_f32_16x16x32_bf16 v[110:113], v[122:125], v[194:197], v[110:113]
	v_mfma_f32_16x16x32_bf16 v[106:109], v[138:141], v[194:197], v[106:109]
	v_mfma_f32_16x16x32_bf16 v[102:105], v[122:125], v[202:205], v[102:105]
	v_mfma_f32_16x16x32_bf16 v[98:101], v[138:141], v[202:205], v[98:101]
	v_mfma_f32_16x16x32_bf16 v[134:137], v[126:129], v[170:173], v[134:137]
	v_mfma_f32_16x16x32_bf16 v[130:133], v[142:145], v[170:173], v[130:133]
	v_mfma_f32_16x16x32_bf16 v[118:121], v[126:129], v[190:193], v[118:121]
	v_mfma_f32_16x16x32_bf16 v[114:117], v[142:145], v[190:193], v[114:117]
	v_mfma_f32_16x16x32_bf16 v[110:113], v[126:129], v[198:201], v[110:113]
	v_mfma_f32_16x16x32_bf16 v[106:109], v[142:145], v[198:201], v[106:109]
	v_mfma_f32_16x16x32_bf16 v[102:105], v[126:129], v[206:209], v[102:105]
	v_mfma_f32_16x16x32_bf16 v[98:101], v[142:145], v[206:209], v[98:101]
	s_setprio 0
	s_barrier
	s_add_i32 s0, 0, 0x14000
	s_add_i32 s1, s62, s36
	v_add_u32_e32 v158, s0, v161
	v_lshl_add_u64 v[186:187], s[24:25], 0, v[4:5]
	s_mov_b32 m0, s1
	ds_read_b128 v[210:213], v158
	ds_read_b128 v[214:217], v158 offset:1024
	ds_read_b128 v[218:221], v158 offset:2048
	ds_read_b128 v[222:225], v158 offset:3072
	global_load_lds_dwordx4 v[186:187], off
	v_lshl_add_u64 v[226:227], s[24:25], 0, v[146:147]
	s_add_i32 m0, s1, 0x2000
	s_nop 0
	global_load_lds_dwordx4 v[226:227], off
	s_barrier
	s_waitcnt lgkmcnt(0)
	s_setprio 1
	s_waitcnt lgkmcnt(0)
	v_mfma_f32_16x16x32_bf16 v[70:73], v[210:213], v[166:169], v[70:73]
	v_mfma_f32_16x16x32_bf16 v[66:69], v[218:221], v[166:169], v[66:69]
	v_mfma_f32_16x16x32_bf16 v[54:57], v[210:213], v[174:177], v[54:57]
	v_mfma_f32_16x16x32_bf16 v[50:53], v[218:221], v[174:177], v[50:53]
	v_mfma_f32_16x16x32_bf16 v[46:49], v[210:213], v[194:197], v[46:49]
	v_mfma_f32_16x16x32_bf16 v[42:45], v[218:221], v[194:197], v[42:45]
	v_mfma_f32_16x16x32_bf16 v[38:41], v[210:213], v[202:205], v[38:41]
	v_mfma_f32_16x16x32_bf16 v[34:37], v[218:221], v[202:205], v[34:37]
	v_mfma_f32_16x16x32_bf16 v[70:73], v[214:217], v[170:173], v[70:73]
	v_mfma_f32_16x16x32_bf16 v[66:69], v[222:225], v[170:173], v[66:69]
	v_mfma_f32_16x16x32_bf16 v[54:57], v[214:217], v[190:193], v[54:57]
	v_mfma_f32_16x16x32_bf16 v[50:53], v[222:225], v[190:193], v[50:53]
	v_mfma_f32_16x16x32_bf16 v[46:49], v[214:217], v[198:201], v[46:49]
	v_mfma_f32_16x16x32_bf16 v[42:45], v[222:225], v[198:201], v[42:45]
	v_mfma_f32_16x16x32_bf16 v[38:41], v[214:217], v[206:209], v[38:41]
	v_mfma_f32_16x16x32_bf16 v[34:37], v[222:225], v[206:209], v[34:37]
	s_setprio 0
	s_mov_b32 m0, s21
	v_lshl_add_u64 v[242:243], s[26:27], 0, v[150:151]
	s_barrier
	ds_read_b128 v[166:169], v165 offset:16384
	ds_read_b128 v[170:173], v165 offset:17408
	ds_read_b128 v[174:177], v165 offset:18432
	ds_read_b128 v[190:193], v165 offset:19456
	ds_read_b128 v[194:197], v165 offset:20480
	ds_read_b128 v[198:201], v165 offset:21504
	ds_read_b128 v[202:205], v165 offset:22528
	ds_read_b128 v[206:209], v165 offset:23552
	global_load_lds_dwordx4 v[242:243], off
	v_lshl_add_u64 v[244:245], s[26:27], 0, v[148:149]
	s_mov_b32 m0, s42
	s_nop 0
	global_load_lds_dwordx4 v[244:245], off
	s_barrier
	s_waitcnt lgkmcnt(0)
	s_setprio 1
	s_waitcnt lgkmcnt(0)
	v_mfma_f32_16x16x32_bf16 v[94:97], v[122:125], v[166:169], v[94:97]
	v_mfma_f32_16x16x32_bf16 v[90:93], v[138:141], v[166:169], v[90:93]
	v_mfma_f32_16x16x32_bf16 v[86:89], v[122:125], v[174:177], v[86:89]
	v_mfma_f32_16x16x32_bf16 v[82:85], v[138:141], v[174:177], v[82:85]
	v_mfma_f32_16x16x32_bf16 v[78:81], v[122:125], v[194:197], v[78:81]
	v_mfma_f32_16x16x32_bf16 v[74:77], v[138:141], v[194:197], v[74:77]
	v_mfma_f32_16x16x32_bf16 v[62:65], v[122:125], v[202:205], v[62:65]
	v_mfma_f32_16x16x32_bf16 v[58:61], v[138:141], v[202:205], v[58:61]
	v_mfma_f32_16x16x32_bf16 v[94:97], v[126:129], v[170:173], v[94:97]
	v_mfma_f32_16x16x32_bf16 v[90:93], v[142:145], v[170:173], v[90:93]
	v_mfma_f32_16x16x32_bf16 v[86:89], v[126:129], v[190:193], v[86:89]
	v_mfma_f32_16x16x32_bf16 v[82:85], v[142:145], v[190:193], v[82:85]
	v_mfma_f32_16x16x32_bf16 v[78:81], v[126:129], v[198:201], v[78:81]
	v_mfma_f32_16x16x32_bf16 v[74:77], v[142:145], v[198:201], v[74:77]
	v_mfma_f32_16x16x32_bf16 v[62:65], v[126:129], v[206:209], v[62:65]
	v_mfma_f32_16x16x32_bf16 v[58:61], v[142:145], v[206:209], v[58:61]
	s_setprio 0
	s_barrier
; #define PG8_STAGE(bufoff, gbase, voff) do { _Pragma("unroll") for (int _i = 0; _i < 2; ++_i) \
;         __builtin_amdgcn_global_load_lds((const unsigned*)((const char*)(gbase) + (voff)[_i]), (LAS unsigned*)(lds + (bufoff) + ldsw + _i * 8192), 16, 0, 0); } while (0)
; #define PG8_LDA(dst, b, h) do { _Pragma("unroll") for (int m = 0; m < 4; ++m) _Pragma("unroll") for (int k = 0; k < 2; ++k) dst[m][k] = *(const LAS bf16x8*)(lds + PG8_SA(b, h) + aoff + m * 2048 + k * 1024); } while (0)
; #define PG8_LDB(dst, b, h) do { _Pragma("unroll") for (int n = 0; n < 2; ++n) _Pragma("unroll") for (int k = 0; k < 2; ++k) dst[n][k] = *(const LAS bf16x8*)(lds + PG8_SB(b, h) + boff + n * 2048 + k * 1024); } while (0)
; #define PG8_MMA(ai, bj, At, Bt) do { __builtin_amdgcn_s_setprio(1); _Pragma("unroll") for (int m = 0; m < 4; ++m) _Pragma("unroll") for (int n = 0; n < 2; ++n) _Pragma("unroll") for (int k = 0; k < 2; ++k) \
;         acc[ai][bj][m][n] = __builtin_amdgcn_mfma_f32_16x16x32_bf16(Bt[n][k], At[m][k], acc[ai][bj][m][n], 0, 0, 0); __builtin_amdgcn_s_setprio(0); } while (0)
; #define PG8_WAIT_V(n) asm volatile("s_waitcnt vmcnt(" #n ")" ::: "memory")
; #define PG8_WAIT_L(n) asm volatile("s_waitcnt lgkmcnt(" #n ")" ::: "memory")
; #define PG8_BAR __builtin_amdgcn_s_barrier()
; #define PG8_SCHED __builtin_amdgcn_sched_barrier(0)
; template <class Epi>
; __device__ __forceinline__ void gemm_phase(LAS unsigned char* lds, const Gemm g, const StaticOrder& S, const Epi& E) {
;     ...
;             PG8_BAR; PG8_WAIT_L(0); PG8_MMA(1, 0, At, B0); PG8_BAR; PG8_SCHED;
;             PG8_STAGE(PG8_SB(0, 1), b2 + hstep, voffB);
;             PG8_WAIT_V(6); PG8_BAR; PG8_MMA(1, 1, At, B1); PG8_BAR;
;             PG8_LDB(B0, 1, 0); PG8_SCHED; PG8_LDA(At, 1, 0); PG8_STAGE(PG8_SA(0, 1), a2 + hstep, voffA);
;             PG8_WAIT_L(8); PG8_BAR; PG8_WAIT_L(0); PG8_MMA(0, 0, At, B0); PG8_BAR; PG8_SCHED;
;             PG8_LDB(B1, 1, 1); PG8_STAGE(PG8_SB(1, 0), b3, voffB);
;             PG8_BAR; PG8_WAIT_L(0); PG8_MMA(0, 1, At, B1); PG8_BAR;
;             PG8_LDA(At, 1, 1); PG8_STAGE(PG8_SA(1, 0), a3, voffA);
;             PG8_BAR; PG8_WAIT_L(0); PG8_MMA(1, 0, At, B0); PG8_BAR; PG8_SCHED;
	s_add_u32 s62, s24, 0x40000
	s_addc_u32 s63, s25, 0
	s_add_i32 s0, s0, s36
	v_lshl_add_u64 v[122:123], s[62:63], 0, v[4:5]
	s_mov_b32 m0, s0
	s_nop 0
	global_load_lds_dwordx4 v[122:123], off
	v_lshl_add_u64 v[122:123], s[62:63], 0, v[146:147]
	s_add_i32 m0, s0, 0x2000
	s_nop 0
	global_load_lds_dwordx4 v[122:123], off
	s_waitcnt vmcnt(6)
	s_barrier
	s_setprio 1
	v_mfma_f32_16x16x32_bf16 v[30:33], v[210:213], v[166:169], v[30:33]
	v_mfma_f32_16x16x32_bf16 v[26:29], v[218:221], v[166:169], v[26:29]
	v_mfma_f32_16x16x32_bf16 v[22:25], v[210:213], v[174:177], v[22:25]
	v_mfma_f32_16x16x32_bf16 v[18:21], v[218:221], v[174:177], v[18:21]
	v_mfma_f32_16x16x32_bf16 v[14:17], v[210:213], v[194:197], v[14:17]
	v_mfma_f32_16x16x32_bf16 v[10:13], v[218:221], v[194:197], v[10:13]
	v_mfma_f32_16x16x32_bf16 v[6:9], v[210:213], v[202:205], v[6:9]
	v_mfma_f32_16x16x32_bf16 v[0:3], v[218:221], v[202:205], v[0:3]
	v_mfma_f32_16x16x32_bf16 v[30:33], v[214:217], v[170:173], v[30:33]
	v_mfma_f32_16x16x32_bf16 v[26:29], v[222:225], v[170:173], v[26:29]
	v_mfma_f32_16x16x32_bf16 v[22:25], v[214:217], v[190:193], v[22:25]
	v_mfma_f32_16x16x32_bf16 v[18:21], v[222:225], v[190:193], v[18:21]
	v_mfma_f32_16x16x32_bf16 v[14:17], v[214:217], v[198:201], v[14:17]
	v_mfma_f32_16x16x32_bf16 v[10:13], v[222:225], v[198:201], v[10:13]
	v_mfma_f32_16x16x32_bf16 v[6:9], v[214:217], v[206:209], v[6:9]
	v_mfma_f32_16x16x32_bf16 v[0:3], v[222:225], v[206:209], v[0:3]
	s_setprio 0
	s_add_i32 s0, 0, 0x18000
	v_add_u32_e32 v142, s0, v161
	s_barrier
	ds_read_b128 v[122:125], v142
	ds_read_b128 v[126:129], v142 offset:1024
	ds_read_b128 v[138:141], v142 offset:2048
	ds_read_b128 v[142:145], v142 offset:3072
	s_add_u32 s26, s26, 0x40000
	s_addc_u32 s27, s27, 0
	s_mov_b32 m0, s43
	v_lshl_add_u64 v[210:211], s[26:27], 0, v[150:151]
	ds_read_b128 v[166:169], v165 offset:32768
	ds_read_b128 v[170:173], v165 offset:33792
	ds_read_b128 v[174:177], v165 offset:34816
	ds_read_b128 v[190:193], v165 offset:35840
	ds_read_b128 v[194:197], v165 offset:36864
	ds_read_b128 v[198:201], v165 offset:37888
	ds_read_b128 v[202:205], v165 offset:38912
	ds_read_b128 v[206:209], v165 offset:39936
	global_load_lds_dwordx4 v[210:211], off
	v_lshl_add_u64 v[210:211], s[26:27], 0, v[148:149]
	s_mov_b32 m0, s48
	s_nop 0
	global_load_lds_dwordx4 v[210:211], off
	s_waitcnt lgkmcnt(8)
	s_barrier
	s_waitcnt lgkmcnt(0)
	s_setprio 1
	s_waitcnt lgkmcnt(0)
	v_mfma_f32_16x16x32_bf16 v[134:137], v[122:125], v[166:169], v[134:137]
	v_mfma_f32_16x16x32_bf16 v[130:133], v[138:141], v[166:169], v[130:133]
	v_mfma_f32_16x16x32_bf16 v[118:121], v[122:125], v[174:177], v[118:121]
	v_mfma_f32_16x16x32_bf16 v[114:117], v[138:141], v[174:177], v[114:117]
	v_mfma_f32_16x16x32_bf16 v[110:113], v[122:125], v[194:197], v[110:113]
	v_mfma_f32_16x16x32_bf16 v[106:109], v[138:141], v[194:197], v[106:109]
	v_mfma_f32_16x16x32_bf16 v[102:105], v[122:125], v[202:205], v[102:105]
	v_mfma_f32_16x16x32_bf16 v[98:101], v[138:141], v[202:205], v[98:101]
	v_mfma_f32_16x16x32_bf16 v[134:137], v[126:129], v[170:173], v[134:137]
	v_mfma_f32_16x16x32_bf16 v[130:133], v[142:145], v[170:173], v[130:133]
	v_mfma_f32_16x16x32_bf16 v[118:121], v[126:129], v[190:193], v[118:121]
	v_mfma_f32_16x16x32_bf16 v[114:117], v[142:145], v[190:193], v[114:117]
	v_mfma_f32_16x16x32_bf16 v[110:113], v[126:129], v[198:201], v[110:113]
	v_mfma_f32_16x16x32_bf16 v[106:109], v[142:145], v[198:201], v[106:109]
	v_mfma_f32_16x16x32_bf16 v[102:105], v[126:129], v[206:209], v[102:105]
	v_mfma_f32_16x16x32_bf16 v[98:101], v[142:145], v[206:209], v[98:101]
	s_setprio 0
	s_barrier
	s_add_i32 s1, 0, 0x1c000
	s_add_i32 s0, s0, s36
	v_add_u32_e32 v158, s1, v161
	v_lshl_add_u64 v[186:187], v[186:187], 0, s[86:87]
	s_mov_b32 m0, s0
	ds_read_b128 v[210:213], v158
	ds_read_b128 v[214:217], v158 offset:1024
	ds_read_b128 v[218:221], v158 offset:2048
	ds_read_b128 v[222:225], v158 offset:3072
	global_load_lds_dwordx4 v[186:187], off
	v_lshl_add_u64 v[186:187], v[226:227], 0, s[86:87]
	s_add_i32 m0, s0, 0x2000
	s_nop 0
	global_load_lds_dwordx4 v[186:187], off
	s_barrier
	s_waitcnt lgkmcnt(0)
	s_setprio 1
	s_waitcnt lgkmcnt(0)
	v_mfma_f32_16x16x32_bf16 v[70:73], v[210:213], v[166:169], v[70:73]
	v_mfma_f32_16x16x32_bf16 v[66:69], v[218:221], v[166:169], v[66:69]
	v_mfma_f32_16x16x32_bf16 v[54:57], v[210:213], v[174:177], v[54:57]
	v_mfma_f32_16x16x32_bf16 v[50:53], v[218:221], v[174:177], v[50:53]
	v_mfma_f32_16x16x32_bf16 v[46:49], v[210:213], v[194:197], v[46:49]
	v_mfma_f32_16x16x32_bf16 v[42:45], v[218:221], v[194:197], v[42:45]
	v_mfma_f32_16x16x32_bf16 v[38:41], v[210:213], v[202:205], v[38:41]
	v_mfma_f32_16x16x32_bf16 v[34:37], v[218:221], v[202:205], v[34:37]
	v_mfma_f32_16x16x32_bf16 v[70:73], v[214:217], v[170:173], v[70:73]
	v_mfma_f32_16x16x32_bf16 v[66:69], v[222:225], v[170:173], v[66:69]
	v_mfma_f32_16x16x32_bf16 v[54:57], v[214:217], v[190:193], v[54:57]
	v_mfma_f32_16x16x32_bf16 v[50:53], v[222:225], v[190:193], v[50:53]
	v_mfma_f32_16x16x32_bf16 v[46:49], v[214:217], v[198:201], v[46:49]
	v_mfma_f32_16x16x32_bf16 v[42:45], v[222:225], v[198:201], v[42:45]
	v_mfma_f32_16x16x32_bf16 v[38:41], v[214:217], v[206:209], v[38:41]
	v_mfma_f32_16x16x32_bf16 v[34:37], v[222:225], v[206:209], v[34:37]
	s_setprio 0
	s_mov_b32 m0, s51
	v_lshl_add_u64 v[186:187], v[242:243], 0, s[86:87]
	s_barrier
	ds_read_b128 v[166:169], v165 offset:49152
	ds_read_b128 v[170:173], v165 offset:50176
	ds_read_b128 v[174:177], v165 offset:51200
	ds_read_b128 v[190:193], v165 offset:52224
	ds_read_b128 v[194:197], v165 offset:53248
	ds_read_b128 v[198:201], v165 offset:54272
	ds_read_b128 v[202:205], v165 offset:55296
	ds_read_b128 v[206:209], v165 offset:56320
	global_load_lds_dwordx4 v[186:187], off
	v_lshl_add_u64 v[186:187], v[244:245], 0, s[86:87]
	s_mov_b32 m0, s54
	s_nop 0
	global_load_lds_dwordx4 v[186:187], off
	s_barrier
; #define PG8_STAGE(bufoff, gbase, voff) do { _Pragma("unroll") for (int _i = 0; _i < 2; ++_i) \
;         __builtin_amdgcn_global_load_lds((const unsigned*)((const char*)(gbase) + (voff)[_i]), (LAS unsigned*)(lds + (bufoff) + ldsw + _i * 8192), 16, 0, 0); } while (0)
; #define PG8_LDA(dst, b, h) do { _Pragma("unroll") for (int m = 0; m < 4; ++m) _Pragma("unroll") for (int k = 0; k < 2; ++k) dst[m][k] = *(const LAS bf16x8*)(lds + PG8_SA(b, h) + aoff + m * 2048 + k * 1024); } while (0)
; #define PG8_MMA(ai, bj, At, Bt) do { __builtin_amdgcn_s_setprio(1); _Pragma("unroll") for (int m = 0; m < 4; ++m) _Pragma("unroll") for (int n = 0; n < 2; ++n) _Pragma("unroll") for (int k = 0; k < 2; ++k) \
;         acc[ai][bj][m][n] = __builtin_amdgcn_mfma_f32_16x16x32_bf16(Bt[n][k], At[m][k], acc[ai][bj][m][n], 0, 0, 0); __builtin_amdgcn_s_setprio(0); } while (0)
; #define PG8_WAIT_V(n) asm volatile("s_waitcnt vmcnt(" #n ")" ::: "memory")
; #define PG8_WAIT_L(n) asm volatile("s_waitcnt lgkmcnt(" #n ")" ::: "memory")
; #define PG8_BAR __builtin_amdgcn_s_barrier()
; #define PG8_SCHED __builtin_amdgcn_sched_barrier(0)
; template <class Epi>
; __device__ __forceinline__ void gemm_phase(LAS unsigned char* lds, const Gemm g, const StaticOrder& S, const Epi& E) {
;     ...
;             PG8_BAR; PG8_WAIT_L(0); PG8_MMA(0, 1, At, B1); PG8_BAR;
;             PG8_LDA(At, 1, 1); PG8_STAGE(PG8_SA(1, 0), a3, voffA);
;             PG8_BAR; PG8_WAIT_L(0); PG8_MMA(1, 0, At, B0); PG8_BAR; PG8_SCHED;
;             PG8_STAGE(PG8_SB(1, 1), b3 + hstep, voffB);
;             PG8_WAIT_V(6); PG8_BAR; PG8_MMA(1, 1, At, B1); PG8_BAR;
;         }
;         E(acc, cur, wr, wc, fr, fq);
; __device__ __forceinline__ void load_rstd(const float* ss, int row0, f32x4& ra, f32x4& rb) {
;     float t[8];
; #pragma unroll
;     for (int i = 0; i < 8; ++i) t[i] = ss[row0 + (i >> 2) * 128 + (i & 3) * 16];
; #pragma unroll
;     for (int i = 0; i < 4; ++i) { ra[i] = __builtin_amdgcn_rsqf(t[i] * (1.f / 1024.f) + 1e-6f); rb[i] = __builtin_amdgcn_rsqf(t[4 + i] * (1.f / 1024.f) + 1e-6f); }
; }
	s_waitcnt lgkmcnt(0)
	s_setprio 1
	s_waitcnt lgkmcnt(0)
	v_mfma_f32_16x16x32_bf16 v[94:97], v[122:125], v[166:169], v[94:97]
	v_mfma_f32_16x16x32_bf16 v[90:93], v[138:141], v[166:169], v[90:93]
	v_mfma_f32_16x16x32_bf16 v[86:89], v[122:125], v[174:177], v[86:89]
	v_mfma_f32_16x16x32_bf16 v[82:85], v[138:141], v[174:177], v[82:85]
	v_mfma_f32_16x16x32_bf16 v[78:81], v[122:125], v[194:197], v[78:81]
	v_mfma_f32_16x16x32_bf16 v[74:77], v[138:141], v[194:197], v[74:77]
	v_mfma_f32_16x16x32_bf16 v[62:65], v[122:125], v[202:205], v[62:65]
	v_mfma_f32_16x16x32_bf16 v[58:61], v[138:141], v[202:205], v[58:61]
	v_mfma_f32_16x16x32_bf16 v[94:97], v[126:129], v[170:173], v[94:97]
	v_mfma_f32_16x16x32_bf16 v[90:93], v[142:145], v[170:173], v[90:93]
	v_mfma_f32_16x16x32_bf16 v[86:89], v[126:129], v[190:193], v[86:89]
	v_mfma_f32_16x16x32_bf16 v[82:85], v[142:145], v[190:193], v[82:85]
	v_mfma_f32_16x16x32_bf16 v[78:81], v[126:129], v[198:201], v[78:81]
	v_mfma_f32_16x16x32_bf16 v[74:77], v[142:145], v[198:201], v[74:77]
	v_mfma_f32_16x16x32_bf16 v[62:65], v[126:129], v[206:209], v[62:65]
	v_mfma_f32_16x16x32_bf16 v[58:61], v[142:145], v[206:209], v[58:61]
	s_setprio 0
	s_barrier
	s_add_u32 s24, s24, 0x40080
	s_addc_u32 s25, s25, 0
	s_add_i32 s0, s1, s36
	v_lshl_add_u64 v[122:123], s[24:25], 0, v[4:5]
	s_mov_b32 m0, s0
	s_nop 0
	global_load_lds_dwordx4 v[122:123], off
	v_lshl_add_u64 v[122:123], s[24:25], 0, v[146:147]
	s_add_i32 m0, s0, 0x2000
	s_nop 0
	global_load_lds_dwordx4 v[122:123], off
	s_waitcnt vmcnt(6)
	s_barrier
	s_setprio 1
	v_mfma_f32_16x16x32_bf16 v[30:33], v[210:213], v[166:169], v[30:33]
	v_mfma_f32_16x16x32_bf16 v[26:29], v[218:221], v[166:169], v[26:29]
	v_mfma_f32_16x16x32_bf16 v[22:25], v[210:213], v[174:177], v[22:25]
	v_mfma_f32_16x16x32_bf16 v[18:21], v[218:221], v[174:177], v[18:21]
	v_mfma_f32_16x16x32_bf16 v[14:17], v[210:213], v[194:197], v[14:17]
	v_mfma_f32_16x16x32_bf16 v[10:13], v[218:221], v[194:197], v[10:13]
	v_mfma_f32_16x16x32_bf16 v[6:9], v[210:213], v[202:205], v[6:9]
	v_mfma_f32_16x16x32_bf16 v[0:3], v[218:221], v[202:205], v[0:3]
	v_mfma_f32_16x16x32_bf16 v[30:33], v[214:217], v[170:173], v[30:33]
	v_mfma_f32_16x16x32_bf16 v[26:29], v[222:225], v[170:173], v[26:29]
	v_mfma_f32_16x16x32_bf16 v[22:25], v[214:217], v[190:193], v[22:25]
	v_mfma_f32_16x16x32_bf16 v[18:21], v[222:225], v[190:193], v[18:21]
	v_mfma_f32_16x16x32_bf16 v[14:17], v[214:217], v[198:201], v[14:17]
	v_mfma_f32_16x16x32_bf16 v[10:13], v[222:225], v[198:201], v[10:13]
	v_mfma_f32_16x16x32_bf16 v[6:9], v[214:217], v[206:209], v[6:9]
	v_mfma_f32_16x16x32_bf16 v[0:3], v[222:225], v[206:209], v[0:3]
	s_setprio 0
	s_add_i32 s61, s61, 2
	s_add_u32 s22, s22, 0x100
	s_addc_u32 s23, s23, 0
	s_add_u32 s59, s59, 0x100
	s_addc_u32 s60, s60, 0
	s_cmp_gt_u32 s61, 13
	s_barrier
	s_cbranch_scc0 .LBB0_2079
	v_lshl_add_u32 v174, s20, 8, v159
	v_ashrrev_i32_e32 v175, 31, v174
	v_lshl_add_u64 v[122:123], v[174:175], 2, s[10:11]
	global_load_dword v190, v[122:123], off
	global_load_dword v191, v[122:123], off offset:64
	global_load_dword v192, v[122:123], off offset:128
	global_load_dword v193, v[122:123], off offset:192
	global_load_dword v194, v[122:123], off offset:512
	global_load_dword v195, v[122:123], off offset:576
	global_load_dword v196, v[122:123], off offset:640
	global_load_dword v197, v[122:123], off offset:704
	s_ashr_i32 s0, s20, 3
	s_mul_hi_i32 s23, s0, s52
	s_mul_i32 s22, s0, s52
	s_lshl_b64 s[22:23], s[22:23], 2
	v_lshl_or_b32 v176, s56, 8, v163
	s_add_u32 s22, s49, s22
	s_addc_u32 s23, s50, s23
	v_ashrrev_i32_e32 v177, 31, v176
	v_lshl_add_u64 v[200:201], v[176:177], 2, s[22:23]
	global_load_dwordx4 v[138:141], v[200:201], off offset:16
	global_load_dwordx4 v[142:145], v[200:201], off
	global_load_dwordx4 v[122:125], v[200:201], off offset:528
	global_load_dwordx4 v[126:129], v[200:201], off offset:512
	s_and_b64 vcc, exec, s[4:5]
	s_mov_b32 s56, s12
	s_mov_b32 s20, s14
	s_mov_b64 s[24:25], s[18:19]
	s_waitcnt vmcnt(4)
	v_fmamk_f32 v202, v190, 0x3a800000, v229
	v_rsq_f32_e32 v172, v202
	v_fmamk_f32 v202, v194, 0x3a800000, v229
	v_rsq_f32_e32 v164, v202
	v_fmamk_f32 v202, v191, 0x3a800000, v229
	v_rsq_f32_e32 v170, v202
	v_fmamk_f32 v202, v195, 0x3a800000, v229
	v_rsq_f32_e32 v162, v202
	v_fmamk_f32 v202, v192, 0x3a800000, v229
	v_rsq_f32_e32 v168, v202
	v_fmamk_f32 v202, v196, 0x3a800000, v229
	v_rsq_f32_e32 v160, v202
	v_fmamk_f32 v202, v193, 0x3a800000, v229
	v_fmamk_f32 v203, v197, 0x3a800000, v229
	v_rsq_f32_e32 v166, v202
	v_rsq_f32_e32 v158, v203
	s_waitcnt vmcnt(0)
; __device__ __forceinline__ unsigned cvt_pk_bf16(float lo, float hi) { unsigned r; asm volatile("s_nop 0\n\tv_cvt_pk_bf16_f32 %0, %1, %2" : "=v"(r) : "v"(lo), "v"(hi)); return r; }
;     __device__ __forceinline__ void operator()(const f32x4 (&acc)[2][2][4][2], const Unit& u, int wr, int wc, int fr, int fq) const {
;     ...
;         for (int bj = 0; bj < 2; ++bj) {
;             const f32x4 s0 = swv[2 * bj], s1 = swv[2 * bj + 1];
; #pragma unroll
;             for (int ai = 0; ai < 2; ++ai)
; #pragma unroll
;                 for (int m = 0; m < 4; ++m) { const int r = row0 + ai * 128 + m * 16;
;                     const float rstd = ai ? rb[m] : ra[m];
;                     const f32x4 v0 = acc[ai][bj][m][0] * rstd + s0, v1 = acc[ai][bj][m][1] * rstd + s1;
;                     uint4 st; st.x = cvt_pk_bf16(v0[0], v0[1]); st.y = cvt_pk_bf16(v0[2], v0[3]); st.z = cvt_pk_bf16(v1[0], v1[1]); st.w = cvt_pk_bf16(v1[2], v1[3]);
;                     *(uint4*)(O + (size_t)r * ldc + col0 + bj * 128) = st; }
	v_pk_fma_f32 v[130:131], v[130:131], v[172:173], v[138:139] op_sel_hi:[1,0,1]
	v_pk_fma_f32 v[136:137], v[136:137], v[172:173], v[144:145] op_sel_hi:[1,0,1]
	v_pk_fma_f32 v[134:135], v[134:135], v[172:173], v[142:143] op_sel_hi:[1,0,1]
	v_pk_fma_f32 v[132:133], v[132:133], v[172:173], v[140:141] op_sel_hi:[1,0,1]
	s_nop 0
	v_cvt_pk_bf16_f32 v134, v134, v135
	s_nop 0
	v_cvt_pk_bf16_f32 v135, v136, v137
	s_nop 0
	v_cvt_pk_bf16_f32 v136, v130, v131
	v_mad_i64_i32 v[130:131], s[22:23], v174, s52, 0
	s_nop 0
	v_cvt_pk_bf16_f32 v137, v132, v133
	v_lshl_add_u64 v[130:131], v[130:131], 1, s[8:9]
	v_lshlrev_b64 v[132:133], 1, v[176:177]
	v_lshl_add_u64 v[130:131], v[130:131], 0, v[132:133]
	global_store_dwordx4 v[130:131], v[134:137], off
	v_pk_fma_f32 v[118:119], v[118:119], v[170:171], v[142:143] op_sel_hi:[1,0,1]
	v_pk_fma_f32 v[114:115], v[114:115], v[170:171], v[138:139] op_sel_hi:[1,0,1]
	v_or_b32_e32 v136, 16, v174
	v_pk_fma_f32 v[120:121], v[120:121], v[170:171], v[144:145] op_sel_hi:[1,0,1]
	v_pk_fma_f32 v[134:135], v[116:117], v[170:171], v[140:141] op_sel_hi:[1,0,1]
	s_nop 0
	v_cvt_pk_bf16_f32 v116, v118, v119
	s_nop 0
	v_cvt_pk_bf16_f32 v117, v120, v121
	s_nop 0
	v_cvt_pk_bf16_f32 v118, v114, v115
	v_mad_i64_i32 v[114:115], s[22:23], v136, s52, 0
	v_lshl_add_u64 v[114:115], v[114:115], 1, s[8:9]
	v_lshl_add_u64 v[114:115], v[114:115], 0, v[132:133]
	s_nop 0
	v_cvt_pk_bf16_f32 v119, v134, v135
	global_store_dwordx4 v[114:115], v[116:119], off
	v_pk_fma_f32 v[110:111], v[110:111], v[168:169], v[142:143] op_sel_hi:[1,0,1]
	v_pk_fma_f32 v[106:107], v[106:107], v[168:169], v[138:139] op_sel_hi:[1,0,1]
	v_or_b32_e32 v118, 32, v174
	v_pk_fma_f32 v[112:113], v[112:113], v[168:169], v[144:145] op_sel_hi:[1,0,1]
	v_pk_fma_f32 v[116:117], v[108:109], v[168:169], v[140:141] op_sel_hi:[1,0,1]
	s_nop 0
	v_cvt_pk_bf16_f32 v108, v110, v111
	s_nop 0
	v_cvt_pk_bf16_f32 v109, v112, v113
	s_nop 0
	v_cvt_pk_bf16_f32 v110, v106, v107
	v_mad_i64_i32 v[106:107], s[22:23], v118, s52, 0
	v_lshl_add_u64 v[106:107], v[106:107], 1, s[8:9]
	v_lshl_add_u64 v[106:107], v[106:107], 0, v[132:133]
	s_nop 0
	v_cvt_pk_bf16_f32 v111, v116, v117
	global_store_dwordx4 v[106:107], v[108:111], off
	v_pk_fma_f32 v[102:103], v[102:103], v[166:167], v[142:143] op_sel_hi:[1,0,1]
	v_pk_fma_f32 v[104:105], v[104:105], v[166:167], v[144:145] op_sel_hi:[1,0,1]
	v_or_b32_e32 v110, 48, v174
	v_pk_fma_f32 v[108:109], v[100:101], v[166:167], v[140:141] op_sel_hi:[1,0,1]
	v_pk_fma_f32 v[100:101], v[98:99], v[166:167], v[138:139] op_sel_hi:[1,0,1]
	s_nop 0
	v_cvt_pk_bf16_f32 v98, v102, v103
	v_mad_i64_i32 v[102:103], s[22:23], v110, s52, 0
	v_lshl_add_u64 v[102:103], v[102:103], 1, s[8:9]
	s_nop 0
	v_cvt_pk_bf16_f32 v99, v104, v105
	s_nop 0
	v_cvt_pk_bf16_f32 v100, v100, v101
	v_lshl_add_u64 v[102:103], v[102:103], 0, v[132:133]
	s_nop 0
	v_cvt_pk_bf16_f32 v101, v108, v109
	global_store_dwordx4 v[102:103], v[98:101], off
	v_pk_fma_f32 v[94:95], v[94:95], v[164:165], v[142:143] op_sel_hi:[1,0,1]
	v_pk_fma_f32 v[96:97], v[96:97], v[164:165], v[144:145] op_sel_hi:[1,0,1]
	v_add_u32_e32 v100, 0x80, v174
	v_pk_fma_f32 v[98:99], v[92:93], v[164:165], v[140:141] op_sel_hi:[1,0,1]
	v_pk_fma_f32 v[92:93], v[90:91], v[164:165], v[138:139] op_sel_hi:[1,0,1]
	s_nop 0
	v_cvt_pk_bf16_f32 v90, v94, v95
	v_mad_i64_i32 v[94:95], s[22:23], v100, s52, 0
	v_lshl_add_u64 v[94:95], v[94:95], 1, s[8:9]
	s_nop 0
	v_cvt_pk_bf16_f32 v91, v96, v97
	s_nop 0
	v_cvt_pk_bf16_f32 v92, v92, v93
	v_lshl_add_u64 v[94:95], v[94:95], 0, v[132:133]
	s_nop 0
	v_cvt_pk_bf16_f32 v93, v98, v99
	global_store_dwordx4 v[94:95], v[90:93], off
	v_pk_fma_f32 v[86:87], v[86:87], v[162:163], v[142:143] op_sel_hi:[1,0,1]
	v_pk_fma_f32 v[88:89], v[88:89], v[162:163], v[144:145] op_sel_hi:[1,0,1]
	v_add_u32_e32 v92, 0x90, v174
	v_pk_fma_f32 v[90:91], v[84:85], v[162:163], v[140:141] op_sel_hi:[1,0,1]
	v_pk_fma_f32 v[84:85], v[82:83], v[162:163], v[138:139] op_sel_hi:[1,0,1]
	s_nop 0
	v_cvt_pk_bf16_f32 v82, v86, v87
	v_mad_i64_i32 v[86:87], s[22:23], v92, s52, 0
	v_lshl_add_u64 v[86:87], v[86:87], 1, s[8:9]
	s_nop 0
	v_cvt_pk_bf16_f32 v83, v88, v89
	s_nop 0
	v_cvt_pk_bf16_f32 v84, v84, v85
	v_lshl_add_u64 v[86:87], v[86:87], 0, v[132:133]
	s_nop 0
	v_cvt_pk_bf16_f32 v85, v90, v91
	global_store_dwordx4 v[86:87], v[82:85], off
	v_pk_fma_f32 v[78:79], v[78:79], v[160:161], v[142:143] op_sel_hi:[1,0,1]
	v_pk_fma_f32 v[80:81], v[80:81], v[160:161], v[144:145] op_sel_hi:[1,0,1]
	v_add_u32_e32 v84, 0xa0, v174
	v_pk_fma_f32 v[82:83], v[76:77], v[160:161], v[140:141] op_sel_hi:[1,0,1]
	v_pk_fma_f32 v[76:77], v[74:75], v[160:161], v[138:139] op_sel_hi:[1,0,1]
	s_nop 0
	v_cvt_pk_bf16_f32 v74, v78, v79
	v_mad_i64_i32 v[78:79], s[22:23], v84, s52, 0
	v_lshl_add_u64 v[78:79], v[78:79], 1, s[8:9]
	s_nop 0
	v_cvt_pk_bf16_f32 v75, v80, v81
	s_nop 0
	v_cvt_pk_bf16_f32 v76, v76, v77
	v_lshl_add_u64 v[78:79], v[78:79], 0, v[132:133]
	s_nop 0
	v_cvt_pk_bf16_f32 v77, v82, v83
	global_store_dwordx4 v[78:79], v[74:77], off
; __device__ __forceinline__ unsigned cvt_pk_bf16(float lo, float hi) { unsigned r; asm volatile("s_nop 0\n\tv_cvt_pk_bf16_f32 %0, %1, %2" : "=v"(r) : "v"(lo), "v"(hi)); return r; }
; #define PG8_WAIT_V(n) asm volatile("s_waitcnt vmcnt(" #n ")" ::: "memory")
; #define PG8_BAR __builtin_amdgcn_s_barrier()
; template <class Epi>
; __device__ __forceinline__ void gemm_phase(LAS unsigned char* lds, const Gemm g, const StaticOrder& S, const Epi& E) {
;     ...
;         if (!has_next) break;
; #pragma unroll
;         for (int a = 0; a < 2; ++a)
; #pragma unroll
;             for (int b = 0; b < 2; ++b)
; #pragma unroll
;                 for (int m = 0; m < 4; ++m)
; #pragma unroll
;                     for (int n = 0; n < 2; ++n) acc[a][b][m][n] = (f32x4){0.f, 0.f, 0.f, 0.f};
;         cur = nxt; cA = nA; cB = nB; ++ui;
;     }
;     PG8_WAIT_V(0);
;     if (wr == 0) PG8_BAR;
;     PG8_BAR;
;     __device__ __forceinline__ void operator()(const f32x4 (&acc)[2][2][4][2], const Unit& u, int wr, int wc, int fr, int fq) const {
;     ...
;         for (int bj = 0; bj < 2; ++bj) {
;             const f32x4 s0 = swv[2 * bj], s1 = swv[2 * bj + 1];
; #pragma unroll
;             for (int ai = 0; ai < 2; ++ai)
; #pragma unroll
;                 for (int m = 0; m < 4; ++m) { const int r = row0 + ai * 128 + m * 16;
;                     const float rstd = ai ? rb[m] : ra[m];
;                     const f32x4 v0 = acc[ai][bj][m][0] * rstd + s0, v1 = acc[ai][bj][m][1] * rstd + s1;
;                     uint4 st; st.x = cvt_pk_bf16(v0[0], v0[1]); st.y = cvt_pk_bf16(v0[2], v0[3]); st.z = cvt_pk_bf16(v1[0], v1[1]); st.w = cvt_pk_bf16(v1[2], v1[3]);
;                     *(uint4*)(O + (size_t)r * ldc + col0 + bj * 128) = st; }
	v_pk_fma_f32 v[62:63], v[62:63], v[158:159], v[142:143] op_sel_hi:[1,0,1]
	v_pk_fma_f32 v[64:65], v[64:65], v[158:159], v[144:145] op_sel_hi:[1,0,1]
	v_add_u32_e32 v76, 0xb0, v174
	v_pk_fma_f32 v[74:75], v[60:61], v[158:159], v[140:141] op_sel_hi:[1,0,1]
	v_pk_fma_f32 v[60:61], v[58:59], v[158:159], v[138:139] op_sel_hi:[1,0,1]
	s_nop 0
	v_cvt_pk_bf16_f32 v58, v62, v63
	v_mad_i64_i32 v[62:63], s[22:23], v76, s52, 0
	v_lshl_add_u64 v[62:63], v[62:63], 1, s[8:9]
	s_nop 0
	v_cvt_pk_bf16_f32 v59, v64, v65
	v_lshl_add_u64 v[62:63], v[62:63], 0, v[132:133]
	s_nop 0
	v_cvt_pk_bf16_f32 v60, v60, v61
	s_nop 0
	v_cvt_pk_bf16_f32 v61, v74, v75
	global_store_dwordx4 v[62:63], v[58:61], off
	v_pk_fma_f32 v[64:65], v[68:69], v[172:173], v[124:125] op_sel_hi:[1,0,1]
	v_pk_fma_f32 v[66:67], v[66:67], v[172:173], v[122:123] op_sel_hi:[1,0,1]
	v_pk_fma_f32 v[58:59], v[70:71], v[172:173], v[126:127] op_sel_hi:[1,0,1]
	v_pk_fma_f32 v[60:61], v[72:73], v[172:173], v[128:129] op_sel_hi:[1,0,1]
	s_nop 0
	v_cvt_pk_bf16_f32 v58, v58, v59
	v_pk_fma_f32 v[56:57], v[56:57], v[170:171], v[128:129] op_sel_hi:[1,0,1]
	s_nop 0
	v_cvt_pk_bf16_f32 v59, v60, v61
	s_nop 0
	v_cvt_pk_bf16_f32 v60, v66, v67
	s_nop 0
	v_cvt_pk_bf16_f32 v61, v64, v65
	global_store_dwordx4 v[130:131], v[58:61], off offset:256
	v_pk_fma_f32 v[54:55], v[54:55], v[170:171], v[126:127] op_sel_hi:[1,0,1]
	v_pk_fma_f32 v[48:49], v[48:49], v[168:169], v[128:129] op_sel_hi:[1,0,1]
	v_pk_fma_f32 v[58:59], v[52:53], v[170:171], v[124:125] op_sel_hi:[1,0,1]
	v_pk_fma_f32 v[52:53], v[50:51], v[170:171], v[122:123] op_sel_hi:[1,0,1]
	s_nop 0
	v_cvt_pk_bf16_f32 v50, v54, v55
	s_nop 0
	v_cvt_pk_bf16_f32 v51, v56, v57
	v_pk_fma_f32 v[46:47], v[46:47], v[168:169], v[126:127] op_sel_hi:[1,0,1]
	s_nop 0
	v_cvt_pk_bf16_f32 v52, v52, v53
	s_nop 0
	v_cvt_pk_bf16_f32 v53, v58, v59
	global_store_dwordx4 v[114:115], v[50:53], off offset:256
	v_pk_fma_f32 v[40:41], v[40:41], v[166:167], v[128:129] op_sel_hi:[1,0,1]
	v_pk_fma_f32 v[38:39], v[38:39], v[166:167], v[126:127] op_sel_hi:[1,0,1]
	v_pk_fma_f32 v[50:51], v[44:45], v[168:169], v[124:125] op_sel_hi:[1,0,1]
	v_pk_fma_f32 v[44:45], v[42:43], v[168:169], v[122:123] op_sel_hi:[1,0,1]
	s_nop 0
	v_cvt_pk_bf16_f32 v42, v46, v47
	s_nop 0
	v_cvt_pk_bf16_f32 v43, v48, v49
	v_pk_fma_f32 v[32:33], v[32:33], v[164:165], v[128:129] op_sel_hi:[1,0,1]
	s_nop 0
	v_cvt_pk_bf16_f32 v44, v44, v45
	s_nop 0
	v_cvt_pk_bf16_f32 v45, v50, v51
	global_store_dwordx4 v[106:107], v[42:45], off offset:256
	v_pk_fma_f32 v[30:31], v[30:31], v[164:165], v[126:127] op_sel_hi:[1,0,1]
	v_pk_fma_f32 v[24:25], v[24:25], v[162:163], v[128:129] op_sel_hi:[1,0,1]
	v_pk_fma_f32 v[42:43], v[36:37], v[166:167], v[124:125] op_sel_hi:[1,0,1]
	v_pk_fma_f32 v[36:37], v[34:35], v[166:167], v[122:123] op_sel_hi:[1,0,1]
	s_nop 0
	v_cvt_pk_bf16_f32 v34, v38, v39
	s_nop 0
	v_cvt_pk_bf16_f32 v35, v40, v41
	v_pk_fma_f32 v[22:23], v[22:23], v[162:163], v[126:127] op_sel_hi:[1,0,1]
	s_nop 0
	v_cvt_pk_bf16_f32 v36, v36, v37
	s_nop 0
	v_cvt_pk_bf16_f32 v37, v42, v43
	global_store_dwordx4 v[102:103], v[34:37], off offset:256
	v_pk_fma_f32 v[16:17], v[16:17], v[160:161], v[128:129] op_sel_hi:[1,0,1]
	v_pk_fma_f32 v[14:15], v[14:15], v[160:161], v[126:127] op_sel_hi:[1,0,1]
	v_pk_fma_f32 v[34:35], v[28:29], v[164:165], v[124:125] op_sel_hi:[1,0,1]
	v_pk_fma_f32 v[28:29], v[26:27], v[164:165], v[122:123] op_sel_hi:[1,0,1]
	s_nop 0
	v_cvt_pk_bf16_f32 v26, v30, v31
	s_nop 0
	v_cvt_pk_bf16_f32 v27, v32, v33
	s_mov_b64 s[22:23], s[16:17]
	s_nop 0
	v_cvt_pk_bf16_f32 v28, v28, v29
	s_nop 0
	v_cvt_pk_bf16_f32 v29, v34, v35
	global_store_dwordx4 v[94:95], v[26:29], off offset:256
	v_pk_fma_f32 v[8:9], v[8:9], v[158:159], v[128:129] op_sel_hi:[1,0,1]
	v_pk_fma_f32 v[6:7], v[6:7], v[158:159], v[126:127] op_sel_hi:[1,0,1]
	v_pk_fma_f32 v[26:27], v[20:21], v[162:163], v[124:125] op_sel_hi:[1,0,1]
	v_pk_fma_f32 v[20:21], v[18:19], v[162:163], v[122:123] op_sel_hi:[1,0,1]
	s_nop 0
	v_cvt_pk_bf16_f32 v18, v22, v23
	s_nop 0
	v_cvt_pk_bf16_f32 v19, v24, v25
	s_nop 0
	s_nop 0
	v_cvt_pk_bf16_f32 v20, v20, v21
	s_nop 0
	v_cvt_pk_bf16_f32 v21, v26, v27
	global_store_dwordx4 v[86:87], v[18:21], off offset:256
	s_nop 1
	v_pk_fma_f32 v[18:19], v[12:13], v[160:161], v[124:125] op_sel_hi:[1,0,1]
	v_pk_fma_f32 v[12:13], v[10:11], v[160:161], v[122:123] op_sel_hi:[1,0,1]
	s_nop 0
	v_cvt_pk_bf16_f32 v10, v14, v15
	s_nop 0
	v_cvt_pk_bf16_f32 v11, v16, v17
	s_nop 0
	s_nop 0
	v_cvt_pk_bf16_f32 v12, v12, v13
	s_nop 0
	v_cvt_pk_bf16_f32 v13, v18, v19
	global_store_dwordx4 v[78:79], v[10:13], off offset:256
	s_nop 1
	v_pk_fma_f32 v[10:11], v[2:3], v[158:159], v[124:125] op_sel_hi:[1,0,1]
	v_pk_fma_f32 v[2:3], v[0:1], v[158:159], v[122:123] op_sel_hi:[1,0,1]
	s_nop 0
	v_cvt_pk_bf16_f32 v0, v6, v7
	s_nop 0
	v_cvt_pk_bf16_f32 v1, v8, v9
	s_nop 0
	s_nop 0
	v_cvt_pk_bf16_f32 v2, v2, v3
	s_nop 0
	v_cvt_pk_bf16_f32 v3, v10, v11
	global_store_dwordx4 v[62:63], v[0:3], off offset:256
	s_cbranch_vccz .LBB0_2076
	s_waitcnt vmcnt(0)
	s_cmpk_gt_u32 s28, 0xff
	s_cbranch_scc1 .LBB0_2083
	s_barrier

; #define PG8_STAGE(bufoff, gbase, voff) do { _Pragma("unroll") for (int _i = 0; _i < 2; ++_i) \
;         __builtin_amdgcn_global_load_lds((const unsigned*)((const char*)(gbase) + (voff)[_i]), (LAS unsigned*)(lds + (bufoff) + ldsw + _i * 8192), 16, 0, 0); } while (0)
; #define PG8_LDA(dst, b, h) do { _Pragma("unroll") for (int m = 0; m < 4; ++m) _Pragma("unroll") for (int k = 0; k < 2; ++k) dst[m][k] = *(const LAS bf16x8*)(lds + PG8_SA(b, h) + aoff + m * 2048 + k * 1024); } while (0)
; #define PG8_LDB(dst, b, h) do { _Pragma("unroll") for (int n = 0; n < 2; ++n) _Pragma("unroll") for (int k = 0; k < 2; ++k) dst[n][k] = *(const LAS bf16x8*)(lds + PG8_SB(b, h) + boff + n * 2048 + k * 1024); } while (0)
; #define PG8_MMA(ai, bj, At, Bt) do { __builtin_amdgcn_s_setprio(1); _Pragma("unroll") for (int m = 0; m < 4; ++m) _Pragma("unroll") for (int n = 0; n < 2; ++n) _Pragma("unroll") for (int k = 0; k < 2; ++k) \
;         acc[ai][bj][m][n] = __builtin_amdgcn_mfma_f32_16x16x32_bf16(Bt[n][k], At[m][k], acc[ai][bj][m][n], 0, 0, 0); __builtin_amdgcn_s_setprio(0); } while (0)
; #define PG8_WAIT_V(n) asm volatile("s_waitcnt vmcnt(" #n ")" ::: "memory")
; #define PG8_WAIT_L(n) asm volatile("s_waitcnt lgkmcnt(" #n ")" ::: "memory")
; template <class Epi>
; __device__ __forceinline__ void gemm_phase(LAS unsigned char* lds, const Gemm g, const StaticOrder& S, const Epi& E) {
;     ...
;         for (int t = 0; t < nt; t += 2) {
;             const bool last = (t == nt - 2);
;             const char* a1 = cA + (size_t)(t + 1) * kstep;
;             const char* a2 = last ? nA : cA + (size_t)(t + 2) * kstep; const char* b2 = last ? nB : cB + (size_t)(t + 2) * kstep;
;             const char* a3 = a2 + kstep; const char* b3 = b2 + kstep;
;             PG8_LDB(B0, 0, 0); PG8_SCHED; PG8_LDA(At, 0, 0); PG8_STAGE(PG8_SA(1, 1), a1 + hstep, voffA);
;             PG8_WAIT_L(8); PG8_BAR; PG8_WAIT_L(0); PG8_MMA(0, 0, At, B0); PG8_BAR; PG8_SCHED;
;             PG8_LDB(B1, 0, 1); PG8_STAGE(PG8_SB(0, 0), b2, voffB);
;             PG8_BAR; PG8_WAIT_L(0); PG8_MMA(0, 1, At, B1); PG8_BAR;
;             PG8_LDA(At, 0, 1); PG8_STAGE(PG8_SA(0, 0), a2, voffA);
;             PG8_BAR; PG8_WAIT_L(0); PG8_MMA(1, 0, At, B0); PG8_BAR; PG8_SCHED;
;             PG8_STAGE(PG8_SB(0, 1), b2 + hstep, voffB);
;             PG8_WAIT_V(6); PG8_BAR; PG8_MMA(1, 1, At, B1); PG8_BAR;
.LBB0_2897:
	s_add_u32 s0, s18, 0xfffc0080
	s_addc_u32 s1, s19, -1
	s_add_i32 s54, 0, 0x10000
	v_add_u32_e32 v78, s54, v161
	ds_read_b128 v[66:69], v78
	ds_read_b128 v[70:73], v78 offset:1024
	ds_read_b128 v[74:77], v78 offset:2048
	ds_read_b128 v[78:81], v78 offset:3072
	s_cmp_eq_u32 s52, 12
	s_cselect_b32 s23, s13, s1
	s_cselect_b32 s22, s48, s0
	s_cselect_b32 s21, s11, s51
	s_cselect_b32 s20, s49, s50
	v_lshl_add_u64 v[156:157], s[18:19], 0, v[152:153]
	s_add_i32 m0, s30, 0xc000
	ds_read_b128 v[168:171], v165
	ds_read_b128 v[172:175], v165 offset:1024
	ds_read_b128 v[190:193], v165 offset:2048
	ds_read_b128 v[194:197], v165 offset:3072
	ds_read_b128 v[198:201], v165 offset:4096
	ds_read_b128 v[202:205], v165 offset:5120
	ds_read_b128 v[206:209], v165 offset:6144
	ds_read_b128 v[210:213], v165 offset:7168
	global_load_lds_dwordx4 v[156:157], off
	v_lshl_add_u64 v[156:157], s[18:19], 0, v[154:155]
	s_add_i32 m0, s30, 0xe000
	s_nop 0
	global_load_lds_dwordx4 v[156:157], off
	s_waitcnt lgkmcnt(8)
	s_barrier
	s_waitcnt lgkmcnt(0)
	s_setprio 1
	s_waitcnt lgkmcnt(0)
	v_mfma_f32_16x16x32_bf16 v[142:145], v[66:69], v[168:171], v[142:145]
	v_mfma_f32_16x16x32_bf16 v[138:141], v[74:77], v[168:171], v[138:141]
	v_mfma_f32_16x16x32_bf16 v[126:129], v[66:69], v[190:193], v[126:129]
	v_mfma_f32_16x16x32_bf16 v[122:125], v[74:77], v[190:193], v[122:125]
	v_mfma_f32_16x16x32_bf16 v[110:113], v[66:69], v[198:201], v[110:113]
	v_mfma_f32_16x16x32_bf16 v[106:109], v[74:77], v[198:201], v[106:109]
	v_mfma_f32_16x16x32_bf16 v[94:97], v[66:69], v[206:209], v[94:97]
	v_mfma_f32_16x16x32_bf16 v[90:93], v[74:77], v[206:209], v[90:93]
	v_mfma_f32_16x16x32_bf16 v[142:145], v[70:73], v[172:175], v[142:145]
	v_mfma_f32_16x16x32_bf16 v[138:141], v[78:81], v[172:175], v[138:141]
	v_mfma_f32_16x16x32_bf16 v[126:129], v[70:73], v[194:197], v[126:129]
	v_mfma_f32_16x16x32_bf16 v[122:125], v[78:81], v[194:197], v[122:125]
	v_mfma_f32_16x16x32_bf16 v[110:113], v[70:73], v[202:205], v[110:113]
	v_mfma_f32_16x16x32_bf16 v[106:109], v[78:81], v[202:205], v[106:109]
	v_mfma_f32_16x16x32_bf16 v[94:97], v[70:73], v[210:213], v[94:97]
	v_mfma_f32_16x16x32_bf16 v[90:93], v[78:81], v[210:213], v[90:93]
	s_setprio 0
	s_barrier
	s_add_i32 s0, 0, 0x14000
	v_add_u32_e32 v156, s0, v161
	s_add_i32 s1, s54, s29
	ds_read_b128 v[214:217], v156
	ds_read_b128 v[218:221], v156 offset:1024
	ds_read_b128 v[222:225], v156 offset:2048
	ds_read_b128 v[242:245], v156 offset:3072
	v_lshl_add_u64 v[156:157], s[20:21], 0, v[4:5]
	s_mov_b32 m0, s1
	v_lshl_add_u64 v[176:177], s[20:21], 0, v[146:147]
	global_load_lds_dwordx4 v[156:157], off
	s_add_i32 m0, s1, 0x2000
	s_nop 0
	global_load_lds_dwordx4 v[176:177], off
	s_barrier
	s_waitcnt lgkmcnt(0)
	s_setprio 1
	s_waitcnt lgkmcnt(0)
	v_mfma_f32_16x16x32_bf16 v[134:137], v[214:217], v[168:171], v[134:137]
	v_mfma_f32_16x16x32_bf16 v[130:133], v[222:225], v[168:171], v[130:133]
	v_mfma_f32_16x16x32_bf16 v[118:121], v[214:217], v[190:193], v[118:121]
	v_mfma_f32_16x16x32_bf16 v[114:117], v[222:225], v[190:193], v[114:117]
	v_mfma_f32_16x16x32_bf16 v[102:105], v[214:217], v[198:201], v[102:105]
	v_mfma_f32_16x16x32_bf16 v[98:101], v[222:225], v[198:201], v[98:101]
	v_mfma_f32_16x16x32_bf16 v[86:89], v[214:217], v[206:209], v[86:89]
	v_mfma_f32_16x16x32_bf16 v[82:85], v[222:225], v[206:209], v[82:85]
	v_mfma_f32_16x16x32_bf16 v[134:137], v[218:221], v[172:175], v[134:137]
	v_mfma_f32_16x16x32_bf16 v[130:133], v[242:245], v[172:175], v[130:133]
	v_mfma_f32_16x16x32_bf16 v[118:121], v[218:221], v[194:197], v[118:121]
	v_mfma_f32_16x16x32_bf16 v[114:117], v[242:245], v[194:197], v[114:117]
	v_mfma_f32_16x16x32_bf16 v[102:105], v[218:221], v[202:205], v[102:105]
	v_mfma_f32_16x16x32_bf16 v[98:101], v[242:245], v[202:205], v[98:101]
	v_mfma_f32_16x16x32_bf16 v[86:89], v[218:221], v[210:213], v[86:89]
	v_mfma_f32_16x16x32_bf16 v[82:85], v[242:245], v[210:213], v[82:85]
	s_setprio 0
	s_mov_b32 m0, s30
	v_lshl_add_u64 v[186:187], s[22:23], 0, v[150:151]
	s_barrier
	ds_read_b128 v[168:171], v165 offset:16384
	ds_read_b128 v[172:175], v165 offset:17408
	ds_read_b128 v[190:193], v165 offset:18432
	ds_read_b128 v[194:197], v165 offset:19456
	ds_read_b128 v[198:201], v165 offset:20480
	ds_read_b128 v[202:205], v165 offset:21504
	ds_read_b128 v[206:209], v165 offset:22528
	ds_read_b128 v[210:213], v165 offset:23552
	global_load_lds_dwordx4 v[186:187], off
	v_lshl_add_u64 v[226:227], s[22:23], 0, v[148:149]
	s_mov_b32 m0, s31
	s_nop 0
	global_load_lds_dwordx4 v[226:227], off
	s_barrier
	s_waitcnt lgkmcnt(0)
	s_setprio 1
	s_waitcnt lgkmcnt(0)
	v_mfma_f32_16x16x32_bf16 v[62:65], v[66:69], v[168:171], v[62:65]
	v_mfma_f32_16x16x32_bf16 v[58:61], v[74:77], v[168:171], v[58:61]
	v_mfma_f32_16x16x32_bf16 v[46:49], v[66:69], v[190:193], v[46:49]
	v_mfma_f32_16x16x32_bf16 v[42:45], v[74:77], v[190:193], v[42:45]
	v_mfma_f32_16x16x32_bf16 v[30:33], v[66:69], v[198:201], v[30:33]
	v_mfma_f32_16x16x32_bf16 v[26:29], v[74:77], v[198:201], v[26:29]
	v_mfma_f32_16x16x32_bf16 v[14:17], v[66:69], v[206:209], v[14:17]
	v_mfma_f32_16x16x32_bf16 v[10:13], v[74:77], v[206:209], v[10:13]
	v_mfma_f32_16x16x32_bf16 v[62:65], v[70:73], v[172:175], v[62:65]
	v_mfma_f32_16x16x32_bf16 v[58:61], v[78:81], v[172:175], v[58:61]
	v_mfma_f32_16x16x32_bf16 v[46:49], v[70:73], v[194:197], v[46:49]
	v_mfma_f32_16x16x32_bf16 v[42:45], v[78:81], v[194:197], v[42:45]
	v_mfma_f32_16x16x32_bf16 v[30:33], v[70:73], v[202:205], v[30:33]
	v_mfma_f32_16x16x32_bf16 v[26:29], v[78:81], v[202:205], v[26:29]
	v_mfma_f32_16x16x32_bf16 v[14:17], v[70:73], v[210:213], v[14:17]
	v_mfma_f32_16x16x32_bf16 v[10:13], v[78:81], v[210:213], v[10:13]
	s_setprio 0
	s_barrier
; #define PG8_STAGE(bufoff, gbase, voff) do { _Pragma("unroll") for (int _i = 0; _i < 2; ++_i) \
;         __builtin_amdgcn_global_load_lds((const unsigned*)((const char*)(gbase) + (voff)[_i]), (LAS unsigned*)(lds + (bufoff) + ldsw + _i * 8192), 16, 0, 0); } while (0)
; #define PG8_LDA(dst, b, h) do { _Pragma("unroll") for (int m = 0; m < 4; ++m) _Pragma("unroll") for (int k = 0; k < 2; ++k) dst[m][k] = *(const LAS bf16x8*)(lds + PG8_SA(b, h) + aoff + m * 2048 + k * 1024); } while (0)
; #define PG8_LDB(dst, b, h) do { _Pragma("unroll") for (int n = 0; n < 2; ++n) _Pragma("unroll") for (int k = 0; k < 2; ++k) dst[n][k] = *(const LAS bf16x8*)(lds + PG8_SB(b, h) + boff + n * 2048 + k * 1024); } while (0)
; #define PG8_MMA(ai, bj, At, Bt) do { __builtin_amdgcn_s_setprio(1); _Pragma("unroll") for (int m = 0; m < 4; ++m) _Pragma("unroll") for (int n = 0; n < 2; ++n) _Pragma("unroll") for (int k = 0; k < 2; ++k) \
;         acc[ai][bj][m][n] = __builtin_amdgcn_mfma_f32_16x16x32_bf16(Bt[n][k], At[m][k], acc[ai][bj][m][n], 0, 0, 0); __builtin_amdgcn_s_setprio(0); } while (0)
; #define PG8_WAIT_V(n) asm volatile("s_waitcnt vmcnt(" #n ")" ::: "memory")
; #define PG8_WAIT_L(n) asm volatile("s_waitcnt lgkmcnt(" #n ")" ::: "memory")
; #define PG8_BAR __builtin_amdgcn_s_barrier()
; #define PG8_SCHED __builtin_amdgcn_sched_barrier(0)
; template <class Epi>
; __device__ __forceinline__ void gemm_phase(LAS unsigned char* lds, const Gemm g, const StaticOrder& S, const Epi& E) {
;     ...
;             PG8_BAR; PG8_WAIT_L(0); PG8_MMA(1, 0, At, B0); PG8_BAR; PG8_SCHED;
;             PG8_STAGE(PG8_SB(0, 1), b2 + hstep, voffB);
;             PG8_WAIT_V(6); PG8_BAR; PG8_MMA(1, 1, At, B1); PG8_BAR;
;             PG8_LDB(B0, 1, 0); PG8_SCHED; PG8_LDA(At, 1, 0); PG8_STAGE(PG8_SA(0, 1), a2 + hstep, voffA);
;             PG8_WAIT_L(8); PG8_BAR; PG8_WAIT_L(0); PG8_MMA(0, 0, At, B0); PG8_BAR; PG8_SCHED;
;             PG8_LDB(B1, 1, 1); PG8_STAGE(PG8_SB(1, 0), b3, voffB);
;             PG8_BAR; PG8_WAIT_L(0); PG8_MMA(0, 1, At, B1); PG8_BAR;
;             PG8_LDA(At, 1, 1); PG8_STAGE(PG8_SA(1, 0), a3, voffA);
;             PG8_BAR; PG8_WAIT_L(0); PG8_MMA(1, 0, At, B0); PG8_BAR; PG8_SCHED;
	s_add_u32 s54, s20, 0x40000
	s_addc_u32 s55, s21, 0
	s_add_i32 s0, s0, s29
	v_lshl_add_u64 v[66:67], s[54:55], 0, v[4:5]
	s_mov_b32 m0, s0
	s_nop 0
	global_load_lds_dwordx4 v[66:67], off
	v_lshl_add_u64 v[66:67], s[54:55], 0, v[146:147]
	s_add_i32 m0, s0, 0x2000
	s_nop 0
	global_load_lds_dwordx4 v[66:67], off
	s_waitcnt vmcnt(6)
	s_barrier
	s_setprio 1
	v_mfma_f32_16x16x32_bf16 v[54:57], v[214:217], v[168:171], v[54:57]
	v_mfma_f32_16x16x32_bf16 v[50:53], v[222:225], v[168:171], v[50:53]
	v_mfma_f32_16x16x32_bf16 v[38:41], v[214:217], v[190:193], v[38:41]
	v_mfma_f32_16x16x32_bf16 v[34:37], v[222:225], v[190:193], v[34:37]
	v_mfma_f32_16x16x32_bf16 v[22:25], v[214:217], v[198:201], v[22:25]
	v_mfma_f32_16x16x32_bf16 v[18:21], v[222:225], v[198:201], v[18:21]
	v_mfma_f32_16x16x32_bf16 v[6:9], v[214:217], v[206:209], v[6:9]
	v_mfma_f32_16x16x32_bf16 v[0:3], v[222:225], v[206:209], v[0:3]
	v_mfma_f32_16x16x32_bf16 v[54:57], v[218:221], v[172:175], v[54:57]
	v_mfma_f32_16x16x32_bf16 v[50:53], v[242:245], v[172:175], v[50:53]
	v_mfma_f32_16x16x32_bf16 v[38:41], v[218:221], v[194:197], v[38:41]
	v_mfma_f32_16x16x32_bf16 v[34:37], v[242:245], v[194:197], v[34:37]
	v_mfma_f32_16x16x32_bf16 v[22:25], v[218:221], v[202:205], v[22:25]
	v_mfma_f32_16x16x32_bf16 v[18:21], v[242:245], v[202:205], v[18:21]
	v_mfma_f32_16x16x32_bf16 v[6:9], v[218:221], v[210:213], v[6:9]
	v_mfma_f32_16x16x32_bf16 v[0:3], v[242:245], v[210:213], v[0:3]
	s_setprio 0
	s_add_i32 s0, 0, 0x18000
	v_add_u32_e32 v78, s0, v161
	s_barrier
	ds_read_b128 v[66:69], v78
	ds_read_b128 v[70:73], v78 offset:1024
	ds_read_b128 v[74:77], v78 offset:2048
	ds_read_b128 v[78:81], v78 offset:3072
	s_add_u32 s22, s22, 0x40000
	s_addc_u32 s23, s23, 0
	s_mov_b32 m0, s34
	v_lshl_add_u64 v[214:215], s[22:23], 0, v[150:151]
	ds_read_b128 v[168:171], v165 offset:32768
	ds_read_b128 v[172:175], v165 offset:33792
	ds_read_b128 v[190:193], v165 offset:34816
	ds_read_b128 v[194:197], v165 offset:35840
	ds_read_b128 v[198:201], v165 offset:36864
	ds_read_b128 v[202:205], v165 offset:37888
	ds_read_b128 v[206:209], v165 offset:38912
	ds_read_b128 v[210:213], v165 offset:39936
	global_load_lds_dwordx4 v[214:215], off
	v_lshl_add_u64 v[214:215], s[22:23], 0, v[148:149]
	s_mov_b32 m0, s35
	s_nop 0
	global_load_lds_dwordx4 v[214:215], off
	s_waitcnt lgkmcnt(8)
	s_barrier
	s_waitcnt lgkmcnt(0)
	s_setprio 1
	s_waitcnt lgkmcnt(0)
	v_mfma_f32_16x16x32_bf16 v[142:145], v[66:69], v[168:171], v[142:145]
	v_mfma_f32_16x16x32_bf16 v[138:141], v[74:77], v[168:171], v[138:141]
	v_mfma_f32_16x16x32_bf16 v[126:129], v[66:69], v[190:193], v[126:129]
	v_mfma_f32_16x16x32_bf16 v[122:125], v[74:77], v[190:193], v[122:125]
	v_mfma_f32_16x16x32_bf16 v[110:113], v[66:69], v[198:201], v[110:113]
	v_mfma_f32_16x16x32_bf16 v[106:109], v[74:77], v[198:201], v[106:109]
	v_mfma_f32_16x16x32_bf16 v[94:97], v[66:69], v[206:209], v[94:97]
	v_mfma_f32_16x16x32_bf16 v[90:93], v[74:77], v[206:209], v[90:93]
	v_mfma_f32_16x16x32_bf16 v[142:145], v[70:73], v[172:175], v[142:145]
	v_mfma_f32_16x16x32_bf16 v[138:141], v[78:81], v[172:175], v[138:141]
	v_mfma_f32_16x16x32_bf16 v[126:129], v[70:73], v[194:197], v[126:129]
	v_mfma_f32_16x16x32_bf16 v[122:125], v[78:81], v[194:197], v[122:125]
	v_mfma_f32_16x16x32_bf16 v[110:113], v[70:73], v[202:205], v[110:113]
	v_mfma_f32_16x16x32_bf16 v[106:109], v[78:81], v[202:205], v[106:109]
	v_mfma_f32_16x16x32_bf16 v[94:97], v[70:73], v[210:213], v[94:97]
	v_mfma_f32_16x16x32_bf16 v[90:93], v[78:81], v[210:213], v[90:93]
	s_setprio 0
	s_barrier
	s_add_i32 s1, 0, 0x1c000
	s_add_i32 s0, s0, s29
	v_add_u32_e32 v158, s1, v161
	v_lshl_add_u64 v[156:157], v[156:157], 0, s[86:87]
	s_mov_b32 m0, s0
	ds_read_b128 v[214:217], v158
	ds_read_b128 v[218:221], v158 offset:1024
	ds_read_b128 v[222:225], v158 offset:2048
	ds_read_b128 v[242:245], v158 offset:3072
	global_load_lds_dwordx4 v[156:157], off
	v_lshl_add_u64 v[156:157], v[176:177], 0, s[86:87]
	s_add_i32 m0, s0, 0x2000
	s_nop 0
	global_load_lds_dwordx4 v[156:157], off
	s_barrier
	s_waitcnt lgkmcnt(0)
	s_setprio 1
	s_waitcnt lgkmcnt(0)
	v_mfma_f32_16x16x32_bf16 v[134:137], v[214:217], v[168:171], v[134:137]
	v_mfma_f32_16x16x32_bf16 v[130:133], v[222:225], v[168:171], v[130:133]
	v_mfma_f32_16x16x32_bf16 v[118:121], v[214:217], v[190:193], v[118:121]
	v_mfma_f32_16x16x32_bf16 v[114:117], v[222:225], v[190:193], v[114:117]
	v_mfma_f32_16x16x32_bf16 v[102:105], v[214:217], v[198:201], v[102:105]
	v_mfma_f32_16x16x32_bf16 v[98:101], v[222:225], v[198:201], v[98:101]
	v_mfma_f32_16x16x32_bf16 v[86:89], v[214:217], v[206:209], v[86:89]
	v_mfma_f32_16x16x32_bf16 v[82:85], v[222:225], v[206:209], v[82:85]
	v_mfma_f32_16x16x32_bf16 v[134:137], v[218:221], v[172:175], v[134:137]
	v_mfma_f32_16x16x32_bf16 v[130:133], v[242:245], v[172:175], v[130:133]
	v_mfma_f32_16x16x32_bf16 v[118:121], v[218:221], v[194:197], v[118:121]
	v_mfma_f32_16x16x32_bf16 v[114:117], v[242:245], v[194:197], v[114:117]
	v_mfma_f32_16x16x32_bf16 v[102:105], v[218:221], v[202:205], v[102:105]
	v_mfma_f32_16x16x32_bf16 v[98:101], v[242:245], v[202:205], v[98:101]
	v_mfma_f32_16x16x32_bf16 v[86:89], v[218:221], v[210:213], v[86:89]
	v_mfma_f32_16x16x32_bf16 v[82:85], v[242:245], v[210:213], v[82:85]
	s_setprio 0
	s_mov_b32 m0, s38
	v_lshl_add_u64 v[156:157], v[186:187], 0, s[86:87]
	s_barrier
	ds_read_b128 v[168:171], v165 offset:49152
	ds_read_b128 v[172:175], v165 offset:50176
	ds_read_b128 v[190:193], v165 offset:51200
	ds_read_b128 v[194:197], v165 offset:52224
	ds_read_b128 v[198:201], v165 offset:53248
	ds_read_b128 v[202:205], v165 offset:54272
	ds_read_b128 v[206:209], v165 offset:55296
	ds_read_b128 v[210:213], v165 offset:56320
	global_load_lds_dwordx4 v[156:157], off
	v_lshl_add_u64 v[156:157], v[226:227], 0, s[86:87]
	s_mov_b32 m0, s39
	s_nop 0
	global_load_lds_dwordx4 v[156:157], off
	s_barrier
; #define PG8_STAGE(bufoff, gbase, voff) do { _Pragma("unroll") for (int _i = 0; _i < 2; ++_i) \
;         __builtin_amdgcn_global_load_lds((const unsigned*)((const char*)(gbase) + (voff)[_i]), (LAS unsigned*)(lds + (bufoff) + ldsw + _i * 8192), 16, 0, 0); } while (0)
; #define PG8_LDA(dst, b, h) do { _Pragma("unroll") for (int m = 0; m < 4; ++m) _Pragma("unroll") for (int k = 0; k < 2; ++k) dst[m][k] = *(const LAS bf16x8*)(lds + PG8_SA(b, h) + aoff + m * 2048 + k * 1024); } while (0)
; #define PG8_MMA(ai, bj, At, Bt) do { __builtin_amdgcn_s_setprio(1); _Pragma("unroll") for (int m = 0; m < 4; ++m) _Pragma("unroll") for (int n = 0; n < 2; ++n) _Pragma("unroll") for (int k = 0; k < 2; ++k) \
;         acc[ai][bj][m][n] = __builtin_amdgcn_mfma_f32_16x16x32_bf16(Bt[n][k], At[m][k], acc[ai][bj][m][n], 0, 0, 0); __builtin_amdgcn_s_setprio(0); } while (0)
; #define PG8_WAIT_V(n) asm volatile("s_waitcnt vmcnt(" #n ")" ::: "memory")
; #define PG8_WAIT_L(n) asm volatile("s_waitcnt lgkmcnt(" #n ")" ::: "memory")
; #define PG8_BAR __builtin_amdgcn_s_barrier()
; #define PG8_SCHED __builtin_amdgcn_sched_barrier(0)
; template <class Epi>
; __device__ __forceinline__ void gemm_phase(LAS unsigned char* lds, const Gemm g, const StaticOrder& S, const Epi& E) {
;     ...
;             PG8_BAR; PG8_WAIT_L(0); PG8_MMA(0, 1, At, B1); PG8_BAR;
;             PG8_LDA(At, 1, 1); PG8_STAGE(PG8_SA(1, 0), a3, voffA);
;             PG8_BAR; PG8_WAIT_L(0); PG8_MMA(1, 0, At, B0); PG8_BAR; PG8_SCHED;
;             PG8_STAGE(PG8_SB(1, 1), b3 + hstep, voffB);
;             PG8_WAIT_V(6); PG8_BAR; PG8_MMA(1, 1, At, B1); PG8_BAR;
;         }
;         E(acc, cur, wr, wc, fr, fq);
;     __device__ __forceinline__ void operator()(const f32x4 (&acc)[2][2][4][2], const Unit& u, int wr, int wc, int fr, int fq) const {
;         const int row0 = u.pm * 256 + wr * 64 + fr, hc0 = u.pn * 128 + wc * 32 + fq * 8;
;         const float* swp = sw + (size_t)(u.pm >> 3) * 5632 + u.pn * 256 + wc * 32 + 8 * fq;
;         f32x4 ra, rb; load_rstd(ss, row0, ra, rb);
;         const f32x4 sg0 = *(const f32x4*)(swp), sg1 = *(const f32x4*)(swp + 4), su0 = *(const f32x4*)(swp + 128), su1 = *(const f32x4*)(swp + 132);
	s_waitcnt lgkmcnt(0)
	s_setprio 1
	s_waitcnt lgkmcnt(0)
	v_mfma_f32_16x16x32_bf16 v[62:65], v[66:69], v[168:171], v[62:65]
	v_mfma_f32_16x16x32_bf16 v[58:61], v[74:77], v[168:171], v[58:61]
	v_mfma_f32_16x16x32_bf16 v[46:49], v[66:69], v[190:193], v[46:49]
	v_mfma_f32_16x16x32_bf16 v[42:45], v[74:77], v[190:193], v[42:45]
	v_mfma_f32_16x16x32_bf16 v[30:33], v[66:69], v[198:201], v[30:33]
	v_mfma_f32_16x16x32_bf16 v[26:29], v[74:77], v[198:201], v[26:29]
	v_mfma_f32_16x16x32_bf16 v[14:17], v[66:69], v[206:209], v[14:17]
	v_mfma_f32_16x16x32_bf16 v[10:13], v[74:77], v[206:209], v[10:13]
	v_mfma_f32_16x16x32_bf16 v[62:65], v[70:73], v[172:175], v[62:65]
	v_mfma_f32_16x16x32_bf16 v[58:61], v[78:81], v[172:175], v[58:61]
	v_mfma_f32_16x16x32_bf16 v[46:49], v[70:73], v[194:197], v[46:49]
	v_mfma_f32_16x16x32_bf16 v[42:45], v[78:81], v[194:197], v[42:45]
	v_mfma_f32_16x16x32_bf16 v[30:33], v[70:73], v[202:205], v[30:33]
	v_mfma_f32_16x16x32_bf16 v[26:29], v[78:81], v[202:205], v[26:29]
	v_mfma_f32_16x16x32_bf16 v[14:17], v[70:73], v[210:213], v[14:17]
	v_mfma_f32_16x16x32_bf16 v[10:13], v[78:81], v[210:213], v[10:13]
	s_setprio 0
	s_barrier
	s_add_u32 s20, s20, 0x40080
	s_addc_u32 s21, s21, 0
	s_add_i32 s0, s1, s29
	v_lshl_add_u64 v[66:67], s[20:21], 0, v[4:5]
	s_mov_b32 m0, s0
	s_nop 0
	global_load_lds_dwordx4 v[66:67], off
	v_lshl_add_u64 v[66:67], s[20:21], 0, v[146:147]
	s_add_i32 m0, s0, 0x2000
	s_nop 0
	global_load_lds_dwordx4 v[66:67], off
	s_waitcnt vmcnt(6)
	s_barrier
	s_setprio 1
	v_mfma_f32_16x16x32_bf16 v[54:57], v[214:217], v[168:171], v[54:57]
	v_mfma_f32_16x16x32_bf16 v[50:53], v[222:225], v[168:171], v[50:53]
	v_mfma_f32_16x16x32_bf16 v[38:41], v[214:217], v[190:193], v[38:41]
	v_mfma_f32_16x16x32_bf16 v[34:37], v[222:225], v[190:193], v[34:37]
	v_mfma_f32_16x16x32_bf16 v[22:25], v[214:217], v[198:201], v[22:25]
	v_mfma_f32_16x16x32_bf16 v[18:21], v[222:225], v[198:201], v[18:21]
	v_mfma_f32_16x16x32_bf16 v[6:9], v[214:217], v[206:209], v[6:9]
	v_mfma_f32_16x16x32_bf16 v[0:3], v[222:225], v[206:209], v[0:3]
	v_mfma_f32_16x16x32_bf16 v[54:57], v[218:221], v[172:175], v[54:57]
	v_mfma_f32_16x16x32_bf16 v[50:53], v[242:245], v[172:175], v[50:53]
	v_mfma_f32_16x16x32_bf16 v[38:41], v[218:221], v[194:197], v[38:41]
	v_mfma_f32_16x16x32_bf16 v[34:37], v[242:245], v[194:197], v[34:37]
	v_mfma_f32_16x16x32_bf16 v[22:25], v[218:221], v[202:205], v[22:25]
	v_mfma_f32_16x16x32_bf16 v[18:21], v[242:245], v[202:205], v[18:21]
	v_mfma_f32_16x16x32_bf16 v[6:9], v[218:221], v[210:213], v[6:9]
	v_mfma_f32_16x16x32_bf16 v[0:3], v[242:245], v[210:213], v[0:3]
	s_setprio 0
	s_add_i32 s52, s52, 2
	s_add_u32 s18, s18, 0x100
	s_addc_u32 s19, s19, 0
	s_add_u32 s50, s50, 0x100
	s_addc_u32 s51, s51, 0
	s_cmp_gt_u32 s52, 13
	s_barrier
	s_cbranch_scc0 .LBB0_2897
	v_lshl_add_u32 v156, s43, 8, v159
	v_ashrrev_i32_e32 v157, 31, v156
	v_lshl_add_u64 v[66:67], v[156:157], 2, s[8:9]
	global_load_dword v190, v[66:67], off
	global_load_dword v191, v[66:67], off offset:64
	global_load_dword v192, v[66:67], off offset:128
	global_load_dword v193, v[66:67], off offset:192
	global_load_dword v194, v[66:67], off offset:512
	global_load_dword v195, v[66:67], off offset:576
	global_load_dword v196, v[66:67], off offset:640
	global_load_dword v197, v[66:67], off offset:704
	s_ashr_i32 s0, s43, 3
	s_mul_hi_i32 s1, s0, 0x5800
	s_mulk_i32 s0, 0x5800
	s_add_u32 s0, s36, s0
	s_addc_u32 s1, s37, s1
	s_lshl_b32 s18, s42, 8
	s_ashr_i32 s19, s18, 31
	s_lshl_b64 s[18:19], s[18:19], 2
	s_add_u32 s0, s0, s18
	s_addc_u32 s1, s1, s19
	s_add_u32 s18, s0, s41
	s_addc_u32 s19, s1, 0
	v_lshl_or_b32 v170, s42, 7, v163
	v_ashrrev_i32_e32 v171, 31, v170
	global_load_dwordx4 v[66:69], v167, s[18:19] offset:16
	global_load_dwordx4 v[74:77], v167, s[18:19]
	global_load_dwordx4 v[70:73], v167, s[18:19] offset:528
	global_load_dwordx4 v[78:81], v167, s[18:19] offset:512
	s_and_b64 vcc, exec, s[4:5]
	s_mov_b32 s42, s10
	s_mov_b32 s43, s12
	s_mov_b64 s[20:21], s[16:17]
	s_waitcnt vmcnt(4)
	v_fmamk_f32 v198, v190, 0x3a800000, v229
	v_rsq_f32_e32 v174, v198
	v_fmamk_f32 v198, v194, 0x3a800000, v229
	v_rsq_f32_e32 v164, v198
	v_fmamk_f32 v198, v191, 0x3a800000, v229
	v_rsq_f32_e32 v172, v198
	v_fmamk_f32 v198, v195, 0x3a800000, v229
	v_rsq_f32_e32 v162, v198
	v_fmamk_f32 v198, v192, 0x3a800000, v229
	v_rsq_f32_e32 v168, v198
	v_fmamk_f32 v198, v196, 0x3a800000, v229
	v_rsq_f32_e32 v160, v198
	v_fmamk_f32 v198, v193, 0x3a800000, v229
	v_fmamk_f32 v199, v197, 0x3a800000, v229
	v_rsq_f32_e32 v166, v198
	v_rsq_f32_e32 v158, v199
	s_waitcnt vmcnt(0)
; __device__ __forceinline__ unsigned cvt_pk_bf16(float lo, float hi) { unsigned r; asm volatile("s_nop 0\n\tv_cvt_pk_bf16_f32 %0, %1, %2" : "=v"(r) : "v"(lo), "v"(hi)); return r; }
; __device__ __forceinline__ float siluf_(float x) { return x * __builtin_amdgcn_rcpf(1.f + __expf(-x)); }
;     __device__ __forceinline__ void operator()(const f32x4 (&acc)[2][2][4][2], const Unit& u, int wr, int wc, int fr, int fq) const {
;     ...
;             for (int m = 0; m < 4; ++m) { const int r = row0 + ai * 128 + m * 16;
;                 const float rstd = ai ? rb[m] : ra[m];
;                 const f32x4 g0 = acc[ai][0][m][0] * rstd + sg0, g1 = acc[ai][0][m][1] * rstd + sg1, u0 = acc[ai][1][m][0] * rstd + su0, u1 = acc[ai][1][m][1] * rstd + su1;
;                 uint4 st; st.x = cvt_pk_bf16(siluf_(g0[0]) * u0[0], siluf_(g0[1]) * u0[1]); st.y = cvt_pk_bf16(siluf_(g0[2]) * u0[2], siluf_(g0[3]) * u0[3]);
;                 st.z = cvt_pk_bf16(siluf_(g1[0]) * u1[0], siluf_(g1[1]) * u1[1]); st.w = cvt_pk_bf16(siluf_(g1[2]) * u1[2], siluf_(g1[3]) * u1[3]);
;                 *(uint4*)(hid + (size_t)r * DFF + hc0) = st; }
	v_pk_fma_f32 v[138:139], v[138:139], v[174:175], v[66:67] op_sel_hi:[1,0,1]
	v_pk_fma_f32 v[142:143], v[142:143], v[174:175], v[74:75] op_sel_hi:[1,0,1]
	v_pk_fma_f32 v[144:145], v[144:145], v[174:175], v[76:77] op_sel_hi:[1,0,1]
	v_pk_fma_f32 v[176:177], v[134:135], v[174:175], v[78:79] op_sel_hi:[1,0,1]
	v_pk_fma_f32 v[134:135], v[132:133], v[174:175], v[72:73] op_sel_hi:[1,0,1]
	v_pk_fma_f32 v[132:133], v[130:131], v[174:175], v[70:71] op_sel_hi:[1,0,1]
	v_mul_f32_e32 v130, 0xbfb8aa3b, v142
	v_mul_f32_e32 v131, 0xbfb8aa3b, v143
	v_exp_f32_e32 v130, v130
	v_exp_f32_e32 v131, v131
	v_pk_fma_f32 v[136:137], v[136:137], v[174:175], v[80:81] op_sel_hi:[1,0,1]
	v_pk_fma_f32 v[140:141], v[140:141], v[174:175], v[68:69] op_sel_hi:[1,0,1]
	v_add_f32_e32 v130, 1.0, v130
	v_add_f32_e32 v131, 1.0, v131
	v_rcp_f32_e32 v130, v130
	v_rcp_f32_e32 v131, v131
	v_pk_fma_f32 v[126:127], v[126:127], v[172:173], v[74:75] op_sel_hi:[1,0,1]
	v_pk_fma_f32 v[118:119], v[118:119], v[172:173], v[78:79] op_sel_hi:[1,0,1]
	v_mul_f32_e32 v130, v142, v130
	v_mul_f32_e32 v131, v143, v131
	v_mul_f32_e32 v130, v176, v130
	v_mul_f32_e32 v131, v177, v131
	s_nop 0
	v_cvt_pk_bf16_f32 v130, v130, v131
	v_mul_f32_e32 v131, 0xbfb8aa3b, v144
	v_exp_f32_e32 v131, v131
	v_pk_fma_f32 v[128:129], v[128:129], v[172:173], v[76:77] op_sel_hi:[1,0,1]
	v_pk_fma_f32 v[120:121], v[120:121], v[172:173], v[80:81] op_sel_hi:[1,0,1]
	v_pk_fma_f32 v[122:123], v[122:123], v[172:173], v[66:67] op_sel_hi:[1,0,1]
	v_add_f32_e32 v131, 1.0, v131
	v_rcp_f32_e32 v131, v131
	v_pk_fma_f32 v[124:125], v[124:125], v[172:173], v[68:69] op_sel_hi:[1,0,1]
	v_pk_fma_f32 v[110:111], v[110:111], v[168:169], v[74:75] op_sel_hi:[1,0,1]
	v_pk_fma_f32 v[102:103], v[102:103], v[168:169], v[78:79] op_sel_hi:[1,0,1]
	v_mul_f32_e32 v131, v144, v131
	v_mul_f32_e32 v131, v136, v131
	v_mul_f32_e32 v136, 0xbfb8aa3b, v145
	v_exp_f32_e32 v136, v136
	v_pk_fma_f32 v[112:113], v[112:113], v[168:169], v[76:77] op_sel_hi:[1,0,1]
	v_pk_fma_f32 v[104:105], v[104:105], v[168:169], v[80:81] op_sel_hi:[1,0,1]
	v_pk_fma_f32 v[106:107], v[106:107], v[168:169], v[66:67] op_sel_hi:[1,0,1]
	v_add_f32_e32 v136, 1.0, v136
	v_rcp_f32_e32 v136, v136
	v_pk_fma_f32 v[108:109], v[108:109], v[168:169], v[68:69] op_sel_hi:[1,0,1]
	v_pk_fma_f32 v[94:95], v[94:95], v[166:167], v[74:75] op_sel_hi:[1,0,1]
	v_pk_fma_f32 v[86:87], v[86:87], v[166:167], v[78:79] op_sel_hi:[1,0,1]
	v_mul_f32_e32 v136, v145, v136
	v_mul_f32_e32 v136, v137, v136
	s_nop 0
	v_cvt_pk_bf16_f32 v131, v131, v136
	v_mul_f32_e32 v136, 0xbfb8aa3b, v138
	v_exp_f32_e32 v136, v136
	v_pk_fma_f32 v[96:97], v[96:97], v[166:167], v[76:77] op_sel_hi:[1,0,1]
	v_pk_fma_f32 v[88:89], v[88:89], v[166:167], v[80:81] op_sel_hi:[1,0,1]
	v_pk_fma_f32 v[90:91], v[90:91], v[166:167], v[66:67] op_sel_hi:[1,0,1]
	v_add_f32_e32 v136, 1.0, v136
	v_rcp_f32_e32 v136, v136
	v_pk_fma_f32 v[92:93], v[92:93], v[166:167], v[68:69] op_sel_hi:[1,0,1]
	v_pk_fma_f32 v[62:63], v[62:63], v[164:165], v[74:75] op_sel_hi:[1,0,1]
	v_pk_fma_f32 v[54:55], v[54:55], v[164:165], v[78:79] op_sel_hi:[1,0,1]
	v_mul_f32_e32 v136, v138, v136
	v_mul_f32_e32 v132, v132, v136
	v_mul_f32_e32 v136, 0xbfb8aa3b, v139
	v_exp_f32_e32 v136, v136
	v_pk_fma_f32 v[64:65], v[64:65], v[164:165], v[76:77] op_sel_hi:[1,0,1]
	v_pk_fma_f32 v[56:57], v[56:57], v[164:165], v[80:81] op_sel_hi:[1,0,1]
	v_pk_fma_f32 v[58:59], v[58:59], v[164:165], v[66:67] op_sel_hi:[1,0,1]
	v_add_f32_e32 v136, 1.0, v136
	v_rcp_f32_e32 v136, v136
	v_pk_fma_f32 v[60:61], v[60:61], v[164:165], v[68:69] op_sel_hi:[1,0,1]
	v_pk_fma_f32 v[46:47], v[46:47], v[162:163], v[74:75] op_sel_hi:[1,0,1]
	v_pk_fma_f32 v[38:39], v[38:39], v[162:163], v[78:79] op_sel_hi:[1,0,1]
	v_mul_f32_e32 v136, v139, v136
	v_mul_f32_e32 v133, v133, v136
	s_nop 0
	v_cvt_pk_bf16_f32 v132, v132, v133
	v_mul_f32_e32 v133, 0xbfb8aa3b, v140
	v_exp_f32_e32 v133, v133
	v_lshlrev_b64 v[136:137], 1, v[170:171]
	v_pk_fma_f32 v[48:49], v[48:49], v[162:163], v[76:77] op_sel_hi:[1,0,1]
	v_pk_fma_f32 v[40:41], v[40:41], v[162:163], v[80:81] op_sel_hi:[1,0,1]
	v_add_f32_e32 v133, 1.0, v133
	v_rcp_f32_e32 v133, v133
	v_pk_fma_f32 v[42:43], v[42:43], v[162:163], v[66:67] op_sel_hi:[1,0,1]
	v_pk_fma_f32 v[44:45], v[44:45], v[162:163], v[68:69] op_sel_hi:[1,0,1]
	v_pk_fma_f32 v[30:31], v[30:31], v[160:161], v[74:75] op_sel_hi:[1,0,1]
	v_mul_f32_e32 v133, v140, v133
	v_mul_f32_e32 v133, v134, v133
	v_mul_f32_e32 v134, 0xbfb8aa3b, v141
	v_exp_f32_e32 v134, v134
	v_pk_fma_f32 v[22:23], v[22:23], v[160:161], v[78:79] op_sel_hi:[1,0,1]
	v_pk_fma_f32 v[32:33], v[32:33], v[160:161], v[76:77] op_sel_hi:[1,0,1]
	v_pk_fma_f32 v[24:25], v[24:25], v[160:161], v[80:81] op_sel_hi:[1,0,1]
	v_add_f32_e32 v134, 1.0, v134
	v_rcp_f32_e32 v134, v134
	v_pk_fma_f32 v[26:27], v[26:27], v[160:161], v[66:67] op_sel_hi:[1,0,1]
	v_pk_fma_f32 v[28:29], v[28:29], v[160:161], v[68:69] op_sel_hi:[1,0,1]
	v_pk_fma_f32 v[14:15], v[14:15], v[158:159], v[74:75] op_sel_hi:[1,0,1]
	v_mul_f32_e32 v134, v141, v134
	v_mul_f32_e32 v134, v135, v134
	s_nop 0
	v_cvt_pk_bf16_f32 v133, v133, v134
	v_mov_b64_e32 v[134:135], s[6:7]
	v_mad_i64_i32 v[138:139], s[18:19], v156, s74, v[134:135]
	v_lshl_add_u64 v[138:139], v[138:139], 0, v[136:137]
	global_store_dwordx4 v[138:139], v[130:133], off
	v_pk_fma_f32 v[6:7], v[6:7], v[158:159], v[78:79] op_sel_hi:[1,0,1]
	v_pk_fma_f32 v[16:17], v[16:17], v[158:159], v[76:77] op_sel_hi:[1,0,1]
	v_pk_fma_f32 v[130:131], v[116:117], v[172:173], v[72:73] op_sel_hi:[1,0,1]
	v_pk_fma_f32 v[116:117], v[114:115], v[172:173], v[70:71] op_sel_hi:[1,0,1]
	v_mul_f32_e32 v114, 0xbfb8aa3b, v126
	v_mul_f32_e32 v115, 0xbfb8aa3b, v127
; __device__ __forceinline__ unsigned cvt_pk_bf16(float lo, float hi) { unsigned r; asm volatile("s_nop 0\n\tv_cvt_pk_bf16_f32 %0, %1, %2" : "=v"(r) : "v"(lo), "v"(hi)); return r; }
; __device__ __forceinline__ float siluf_(float x) { return x * __builtin_amdgcn_rcpf(1.f + __expf(-x)); }
;     __device__ __forceinline__ void operator()(const f32x4 (&acc)[2][2][4][2], const Unit& u, int wr, int wc, int fr, int fq) const {
;     ...
;             for (int m = 0; m < 4; ++m) { const int r = row0 + ai * 128 + m * 16;
;                 const float rstd = ai ? rb[m] : ra[m];
;                 const f32x4 g0 = acc[ai][0][m][0] * rstd + sg0, g1 = acc[ai][0][m][1] * rstd + sg1, u0 = acc[ai][1][m][0] * rstd + su0, u1 = acc[ai][1][m][1] * rstd + su1;
;                 uint4 st; st.x = cvt_pk_bf16(siluf_(g0[0]) * u0[0], siluf_(g0[1]) * u0[1]); st.y = cvt_pk_bf16(siluf_(g0[2]) * u0[2], siluf_(g0[3]) * u0[3]);
;                 st.z = cvt_pk_bf16(siluf_(g1[0]) * u1[0], siluf_(g1[1]) * u1[1]); st.w = cvt_pk_bf16(siluf_(g1[2]) * u1[2], siluf_(g1[3]) * u1[3]);
;                 *(uint4*)(hid + (size_t)r * DFF + hc0) = st; }
	v_exp_f32_e32 v114, v114
	v_exp_f32_e32 v115, v115
	v_or_b32_e32 v132, 16, v156
	v_pk_fma_f32 v[8:9], v[8:9], v[158:159], v[80:81] op_sel_hi:[1,0,1]
	v_add_f32_e32 v114, 1.0, v114
	v_add_f32_e32 v115, 1.0, v115
	v_rcp_f32_e32 v114, v114
	v_rcp_f32_e32 v115, v115
	v_pk_fma_f32 v[10:11], v[10:11], v[158:159], v[66:67] op_sel_hi:[1,0,1]
	v_pk_fma_f32 v[12:13], v[12:13], v[158:159], v[68:69] op_sel_hi:[1,0,1]
	v_mul_f32_e32 v114, v126, v114
	v_mul_f32_e32 v115, v127, v115
	v_mul_f32_e32 v114, v118, v114
	v_mul_f32_e32 v115, v119, v115
	s_nop 0
	v_cvt_pk_bf16_f32 v114, v114, v115
	v_mul_f32_e32 v115, 0xbfb8aa3b, v128
	v_mul_f32_e32 v118, 0xbfb8aa3b, v129
	v_exp_f32_e32 v115, v115
	v_exp_f32_e32 v118, v118
	v_add_f32_e32 v115, 1.0, v115
	v_add_f32_e32 v118, 1.0, v118
	v_rcp_f32_e32 v115, v115
	v_rcp_f32_e32 v118, v118
	v_mul_f32_e32 v115, v128, v115
	v_mul_f32_e32 v118, v129, v118
	v_mul_f32_e32 v115, v120, v115
	v_mul_f32_e32 v118, v121, v118
	s_nop 0
	v_cvt_pk_bf16_f32 v115, v115, v118
	v_mul_f32_e32 v118, 0xbfb8aa3b, v122
	v_exp_f32_e32 v118, v118
	s_nop 0
	v_add_f32_e32 v118, 1.0, v118
	v_rcp_f32_e32 v118, v118
	s_nop 0
	v_mul_f32_e32 v118, v122, v118
	v_mul_f32_e32 v116, v116, v118
	v_mul_f32_e32 v118, 0xbfb8aa3b, v123
	v_exp_f32_e32 v118, v118
	s_nop 0
	v_add_f32_e32 v118, 1.0, v118
	v_rcp_f32_e32 v118, v118
	s_nop 0
	v_mul_f32_e32 v118, v123, v118
	v_mul_f32_e32 v117, v117, v118
	s_nop 0
	v_cvt_pk_bf16_f32 v116, v116, v117
	v_mul_f32_e32 v117, 0xbfb8aa3b, v124
	v_mul_f32_e32 v118, 0xbfb8aa3b, v125
	v_exp_f32_e32 v117, v117
	v_exp_f32_e32 v118, v118
	v_add_f32_e32 v117, 1.0, v117
	v_add_f32_e32 v118, 1.0, v118
	v_rcp_f32_e32 v117, v117
	v_rcp_f32_e32 v118, v118
	v_mul_f32_e32 v117, v124, v117
	v_mul_f32_e32 v118, v125, v118
	v_mul_f32_e32 v117, v130, v117
	v_mul_f32_e32 v118, v131, v118
	s_nop 0
	v_cvt_pk_bf16_f32 v117, v117, v118
	v_mad_i64_i32 v[118:119], s[18:19], v132, s74, v[134:135]
	v_lshl_add_u64 v[118:119], v[118:119], 0, v[136:137]
	global_store_dwordx4 v[118:119], v[114:117], off
	s_nop 1
	v_pk_fma_f32 v[114:115], v[100:101], v[168:169], v[72:73] op_sel_hi:[1,0,1]
	v_pk_fma_f32 v[100:101], v[98:99], v[168:169], v[70:71] op_sel_hi:[1,0,1]
	v_mul_f32_e32 v98, 0xbfb8aa3b, v110
	v_mul_f32_e32 v99, 0xbfb8aa3b, v111
	v_exp_f32_e32 v98, v98
	v_exp_f32_e32 v99, v99
	v_or_b32_e32 v116, 32, v156
	v_add_f32_e32 v98, 1.0, v98
	v_add_f32_e32 v99, 1.0, v99
	v_rcp_f32_e32 v98, v98
	v_rcp_f32_e32 v99, v99
	v_mul_f32_e32 v98, v110, v98
	v_mul_f32_e32 v99, v111, v99
	v_mul_f32_e32 v98, v102, v98
	v_mul_f32_e32 v99, v103, v99
	s_nop 0
	v_cvt_pk_bf16_f32 v98, v98, v99
	v_mul_f32_e32 v99, 0xbfb8aa3b, v112
	v_mul_f32_e32 v102, 0xbfb8aa3b, v113
	v_exp_f32_e32 v99, v99
	v_exp_f32_e32 v102, v102
	v_add_f32_e32 v99, 1.0, v99
	v_add_f32_e32 v102, 1.0, v102
	v_rcp_f32_e32 v99, v99
	v_rcp_f32_e32 v102, v102
	v_mul_f32_e32 v99, v112, v99
	v_mul_f32_e32 v102, v113, v102
	v_mul_f32_e32 v99, v104, v99
	v_mul_f32_e32 v102, v105, v102
	s_nop 0
	v_cvt_pk_bf16_f32 v99, v99, v102
	v_mul_f32_e32 v102, 0xbfb8aa3b, v106
	v_exp_f32_e32 v102, v102
	s_nop 0
	v_add_f32_e32 v102, 1.0, v102
	v_rcp_f32_e32 v102, v102
	s_nop 0
	v_mul_f32_e32 v102, v106, v102
	v_mul_f32_e32 v100, v100, v102
	v_mul_f32_e32 v102, 0xbfb8aa3b, v107
	v_exp_f32_e32 v102, v102
	s_nop 0
	v_add_f32_e32 v102, 1.0, v102
	v_rcp_f32_e32 v102, v102
	s_nop 0
	v_mul_f32_e32 v102, v107, v102
	v_mul_f32_e32 v101, v101, v102
	s_nop 0
	v_cvt_pk_bf16_f32 v100, v100, v101
	v_mul_f32_e32 v101, 0xbfb8aa3b, v108
	v_mul_f32_e32 v102, 0xbfb8aa3b, v109
	v_exp_f32_e32 v101, v101
	v_exp_f32_e32 v102, v102
	v_add_f32_e32 v101, 1.0, v101
	v_add_f32_e32 v102, 1.0, v102
	v_rcp_f32_e32 v101, v101
	v_rcp_f32_e32 v102, v102
	v_mul_f32_e32 v101, v108, v101
	v_mul_f32_e32 v102, v109, v102
	v_mul_f32_e32 v101, v114, v101
	v_mul_f32_e32 v102, v115, v102
	s_nop 0
	v_cvt_pk_bf16_f32 v101, v101, v102
	v_mad_i64_i32 v[102:103], s[18:19], v116, s74, v[134:135]
	v_lshl_add_u64 v[102:103], v[102:103], 0, v[136:137]
	global_store_dwordx4 v[102:103], v[98:101], off
	s_nop 1
	v_pk_fma_f32 v[98:99], v[84:85], v[166:167], v[72:73] op_sel_hi:[1,0,1]
	v_pk_fma_f32 v[84:85], v[82:83], v[166:167], v[70:71] op_sel_hi:[1,0,1]
	v_mul_f32_e32 v82, 0xbfb8aa3b, v94
	v_mul_f32_e32 v83, 0xbfb8aa3b, v95
	v_exp_f32_e32 v82, v82
	v_exp_f32_e32 v83, v83
	v_or_b32_e32 v100, 48, v156
	v_add_f32_e32 v82, 1.0, v82
	v_add_f32_e32 v83, 1.0, v83
	v_rcp_f32_e32 v82, v82
	v_rcp_f32_e32 v83, v83
	v_mul_f32_e32 v82, v94, v82
	v_mul_f32_e32 v83, v95, v83
	v_mul_f32_e32 v82, v86, v82
	v_mul_f32_e32 v83, v87, v83
	s_nop 0
	v_cvt_pk_bf16_f32 v82, v82, v83
	v_mul_f32_e32 v83, 0xbfb8aa3b, v96
	v_mul_f32_e32 v86, 0xbfb8aa3b, v97
	v_exp_f32_e32 v83, v83
	v_exp_f32_e32 v86, v86
	v_add_f32_e32 v83, 1.0, v83
	v_add_f32_e32 v86, 1.0, v86
	v_rcp_f32_e32 v83, v83
	v_rcp_f32_e32 v86, v86
	v_mul_f32_e32 v83, v96, v83
	v_mul_f32_e32 v86, v97, v86
	v_mul_f32_e32 v83, v88, v83
	v_mul_f32_e32 v86, v89, v86
	s_nop 0
	v_cvt_pk_bf16_f32 v83, v83, v86
	v_mul_f32_e32 v86, 0xbfb8aa3b, v90
	v_exp_f32_e32 v86, v86
	s_nop 0
	v_add_f32_e32 v86, 1.0, v86
	v_rcp_f32_e32 v86, v86
	s_nop 0
	v_mul_f32_e32 v86, v90, v86
	v_mul_f32_e32 v84, v84, v86
	v_mul_f32_e32 v86, 0xbfb8aa3b, v91
	v_exp_f32_e32 v86, v86
	s_nop 0
	v_add_f32_e32 v86, 1.0, v86
	v_rcp_f32_e32 v86, v86
	s_nop 0
	v_mul_f32_e32 v86, v91, v86
	v_mul_f32_e32 v85, v85, v86
	s_nop 0
	v_cvt_pk_bf16_f32 v84, v84, v85
	v_mul_f32_e32 v85, 0xbfb8aa3b, v92
	v_mul_f32_e32 v86, 0xbfb8aa3b, v93
	v_exp_f32_e32 v85, v85
	v_exp_f32_e32 v86, v86
	v_add_f32_e32 v85, 1.0, v85
	v_add_f32_e32 v86, 1.0, v86
	v_rcp_f32_e32 v85, v85
	v_rcp_f32_e32 v86, v86
; __device__ __forceinline__ unsigned cvt_pk_bf16(float lo, float hi) { unsigned r; asm volatile("s_nop 0\n\tv_cvt_pk_bf16_f32 %0, %1, %2" : "=v"(r) : "v"(lo), "v"(hi)); return r; }
; __device__ __forceinline__ float siluf_(float x) { return x * __builtin_amdgcn_rcpf(1.f + __expf(-x)); }
;     __device__ __forceinline__ void operator()(const f32x4 (&acc)[2][2][4][2], const Unit& u, int wr, int wc, int fr, int fq) const {
;     ...
;             for (int m = 0; m < 4; ++m) { const int r = row0 + ai * 128 + m * 16;
;                 const float rstd = ai ? rb[m] : ra[m];
;                 const f32x4 g0 = acc[ai][0][m][0] * rstd + sg0, g1 = acc[ai][0][m][1] * rstd + sg1, u0 = acc[ai][1][m][0] * rstd + su0, u1 = acc[ai][1][m][1] * rstd + su1;
;                 uint4 st; st.x = cvt_pk_bf16(siluf_(g0[0]) * u0[0], siluf_(g0[1]) * u0[1]); st.y = cvt_pk_bf16(siluf_(g0[2]) * u0[2], siluf_(g0[3]) * u0[3]);
;                 st.z = cvt_pk_bf16(siluf_(g1[0]) * u1[0], siluf_(g1[1]) * u1[1]); st.w = cvt_pk_bf16(siluf_(g1[2]) * u1[2], siluf_(g1[3]) * u1[3]);
;                 *(uint4*)(hid + (size_t)r * DFF + hc0) = st; }
	v_mul_f32_e32 v85, v92, v85
	v_mul_f32_e32 v86, v93, v86
	v_mul_f32_e32 v85, v98, v85
	v_mul_f32_e32 v86, v99, v86
	s_nop 0
	v_cvt_pk_bf16_f32 v85, v85, v86
	v_mad_i64_i32 v[86:87], s[18:19], v100, s74, v[134:135]
	v_lshl_add_u64 v[86:87], v[86:87], 0, v[136:137]
	global_store_dwordx4 v[86:87], v[82:85], off
	s_nop 1
	v_pk_fma_f32 v[82:83], v[52:53], v[164:165], v[72:73] op_sel_hi:[1,0,1]
	v_pk_fma_f32 v[52:53], v[50:51], v[164:165], v[70:71] op_sel_hi:[1,0,1]
	v_mul_f32_e32 v50, 0xbfb8aa3b, v62
	v_mul_f32_e32 v51, 0xbfb8aa3b, v63
	v_exp_f32_e32 v50, v50
	v_exp_f32_e32 v51, v51
	v_add_u32_e32 v84, 0x80, v156
	v_add_f32_e32 v50, 1.0, v50
	v_add_f32_e32 v51, 1.0, v51
	v_rcp_f32_e32 v50, v50
	v_rcp_f32_e32 v51, v51
	v_mul_f32_e32 v50, v62, v50
	v_mul_f32_e32 v51, v63, v51
	v_mul_f32_e32 v50, v54, v50
	v_mul_f32_e32 v51, v55, v51
	s_nop 0
	v_cvt_pk_bf16_f32 v50, v50, v51
	v_mul_f32_e32 v51, 0xbfb8aa3b, v64
	v_mul_f32_e32 v54, 0xbfb8aa3b, v65
	v_exp_f32_e32 v51, v51
	v_exp_f32_e32 v54, v54
	v_add_f32_e32 v51, 1.0, v51
	v_add_f32_e32 v54, 1.0, v54
	v_rcp_f32_e32 v51, v51
	v_rcp_f32_e32 v54, v54
	v_mul_f32_e32 v51, v64, v51
	v_mul_f32_e32 v54, v65, v54
	v_mul_f32_e32 v51, v56, v51
	v_mul_f32_e32 v54, v57, v54
	s_nop 0
	v_cvt_pk_bf16_f32 v51, v51, v54
	v_mul_f32_e32 v54, 0xbfb8aa3b, v58
	v_exp_f32_e32 v54, v54
	s_nop 0
	v_add_f32_e32 v54, 1.0, v54
	v_rcp_f32_e32 v54, v54
	s_nop 0
	v_mul_f32_e32 v54, v58, v54
	v_mul_f32_e32 v52, v52, v54
	v_mul_f32_e32 v54, 0xbfb8aa3b, v59
	v_exp_f32_e32 v54, v54
	s_nop 0
	v_add_f32_e32 v54, 1.0, v54
	v_rcp_f32_e32 v54, v54
	s_nop 0
	v_mul_f32_e32 v54, v59, v54
	v_mul_f32_e32 v53, v53, v54
	s_nop 0
	v_cvt_pk_bf16_f32 v52, v52, v53
	v_mul_f32_e32 v53, 0xbfb8aa3b, v60
	v_mul_f32_e32 v54, 0xbfb8aa3b, v61
	v_exp_f32_e32 v53, v53
	v_exp_f32_e32 v54, v54
	v_add_f32_e32 v53, 1.0, v53
	v_add_f32_e32 v54, 1.0, v54
	v_rcp_f32_e32 v53, v53
	v_rcp_f32_e32 v54, v54
	v_mul_f32_e32 v53, v60, v53
	v_mul_f32_e32 v54, v61, v54
	v_mul_f32_e32 v53, v82, v53
	v_mul_f32_e32 v54, v83, v54
	s_nop 0
	v_cvt_pk_bf16_f32 v53, v53, v54
	v_mad_i64_i32 v[54:55], s[18:19], v84, s74, v[134:135]
	v_lshl_add_u64 v[54:55], v[54:55], 0, v[136:137]
	global_store_dwordx4 v[54:55], v[50:53], off
	s_nop 1
	v_pk_fma_f32 v[50:51], v[36:37], v[162:163], v[72:73] op_sel_hi:[1,0,1]
	v_pk_fma_f32 v[36:37], v[34:35], v[162:163], v[70:71] op_sel_hi:[1,0,1]
	v_mul_f32_e32 v34, 0xbfb8aa3b, v46
	v_mul_f32_e32 v35, 0xbfb8aa3b, v47
	v_exp_f32_e32 v34, v34
	v_exp_f32_e32 v35, v35
	v_add_u32_e32 v52, 0x90, v156
	v_add_f32_e32 v34, 1.0, v34
	v_add_f32_e32 v35, 1.0, v35
	v_rcp_f32_e32 v34, v34
	v_rcp_f32_e32 v35, v35
	v_mul_f32_e32 v34, v46, v34
	v_mul_f32_e32 v35, v47, v35
	v_mul_f32_e32 v34, v38, v34
	v_mul_f32_e32 v35, v39, v35
	s_nop 0
	v_cvt_pk_bf16_f32 v34, v34, v35
	v_mul_f32_e32 v35, 0xbfb8aa3b, v48
	v_mul_f32_e32 v38, 0xbfb8aa3b, v49
	v_exp_f32_e32 v35, v35
	v_exp_f32_e32 v38, v38
	v_add_f32_e32 v35, 1.0, v35
	v_add_f32_e32 v38, 1.0, v38
	v_rcp_f32_e32 v35, v35
	v_rcp_f32_e32 v38, v38
	v_mul_f32_e32 v35, v48, v35
	v_mul_f32_e32 v38, v49, v38
	v_mul_f32_e32 v35, v40, v35
	v_mul_f32_e32 v38, v41, v38
	s_nop 0
	v_cvt_pk_bf16_f32 v35, v35, v38
	v_mul_f32_e32 v38, 0xbfb8aa3b, v42
	v_exp_f32_e32 v38, v38
	s_nop 0
	v_add_f32_e32 v38, 1.0, v38
	v_rcp_f32_e32 v38, v38
	s_nop 0
	v_mul_f32_e32 v38, v42, v38
	v_mul_f32_e32 v36, v36, v38
	v_mul_f32_e32 v38, 0xbfb8aa3b, v43
	v_exp_f32_e32 v38, v38
	s_nop 0
	v_add_f32_e32 v38, 1.0, v38
	v_rcp_f32_e32 v38, v38
	s_nop 0
	v_mul_f32_e32 v38, v43, v38
	v_mul_f32_e32 v37, v37, v38
	s_nop 0
	v_cvt_pk_bf16_f32 v36, v36, v37
	v_mul_f32_e32 v37, 0xbfb8aa3b, v44
	v_mul_f32_e32 v38, 0xbfb8aa3b, v45
	v_exp_f32_e32 v37, v37
	v_exp_f32_e32 v38, v38
	v_add_f32_e32 v37, 1.0, v37
	v_add_f32_e32 v38, 1.0, v38
	v_rcp_f32_e32 v37, v37
	v_rcp_f32_e32 v38, v38
	v_mul_f32_e32 v37, v44, v37
	v_mul_f32_e32 v38, v45, v38
	v_mul_f32_e32 v37, v50, v37
	v_mul_f32_e32 v38, v51, v38
	s_nop 0
	v_cvt_pk_bf16_f32 v37, v37, v38
; __device__ __forceinline__ unsigned cvt_pk_bf16(float lo, float hi) { unsigned r; asm volatile("s_nop 0\n\tv_cvt_pk_bf16_f32 %0, %1, %2" : "=v"(r) : "v"(lo), "v"(hi)); return r; }
; __device__ __forceinline__ float siluf_(float x) { return x * __builtin_amdgcn_rcpf(1.f + __expf(-x)); }
; #define PG8_WAIT_V(n) asm volatile("s_waitcnt vmcnt(" #n ")" ::: "memory")
; #define PG8_BAR __builtin_amdgcn_s_barrier()
; template <class Epi>
; __device__ __forceinline__ void gemm_phase(LAS unsigned char* lds, const Gemm g, const StaticOrder& S, const Epi& E) {
;     ...
;         if (!has_next) break;
; #pragma unroll
;         for (int a = 0; a < 2; ++a)
; #pragma unroll
;             for (int b = 0; b < 2; ++b)
; #pragma unroll
;                 for (int m = 0; m < 4; ++m)
; #pragma unroll
;                     for (int n = 0; n < 2; ++n) acc[a][b][m][n] = (f32x4){0.f, 0.f, 0.f, 0.f};
;         cur = nxt; cA = nA; cB = nB; ++ui;
;     }
;     PG8_WAIT_V(0);
;     if (wr == 0) PG8_BAR;
;     PG8_BAR;
;     __device__ __forceinline__ void operator()(const f32x4 (&acc)[2][2][4][2], const Unit& u, int wr, int wc, int fr, int fq) const {
;     ...
;             for (int m = 0; m < 4; ++m) { const int r = row0 + ai * 128 + m * 16;
;                 const float rstd = ai ? rb[m] : ra[m];
;                 const f32x4 g0 = acc[ai][0][m][0] * rstd + sg0, g1 = acc[ai][0][m][1] * rstd + sg1, u0 = acc[ai][1][m][0] * rstd + su0, u1 = acc[ai][1][m][1] * rstd + su1;
;                 uint4 st; st.x = cvt_pk_bf16(siluf_(g0[0]) * u0[0], siluf_(g0[1]) * u0[1]); st.y = cvt_pk_bf16(siluf_(g0[2]) * u0[2], siluf_(g0[3]) * u0[3]);
;                 st.z = cvt_pk_bf16(siluf_(g1[0]) * u1[0], siluf_(g1[1]) * u1[1]); st.w = cvt_pk_bf16(siluf_(g1[2]) * u1[2], siluf_(g1[3]) * u1[3]);
;                 *(uint4*)(hid + (size_t)r * DFF + hc0) = st; }
	v_mad_i64_i32 v[38:39], s[18:19], v52, s74, v[134:135]
	v_lshl_add_u64 v[38:39], v[38:39], 0, v[136:137]
	global_store_dwordx4 v[38:39], v[34:37], off
	s_nop 1
	v_pk_fma_f32 v[34:35], v[20:21], v[160:161], v[72:73] op_sel_hi:[1,0,1]
	v_pk_fma_f32 v[20:21], v[18:19], v[160:161], v[70:71] op_sel_hi:[1,0,1]
	v_mul_f32_e32 v18, 0xbfb8aa3b, v30
	v_mul_f32_e32 v19, 0xbfb8aa3b, v31
	v_exp_f32_e32 v18, v18
	v_exp_f32_e32 v19, v19
	v_add_u32_e32 v36, 0xa0, v156
	v_add_f32_e32 v18, 1.0, v18
	v_add_f32_e32 v19, 1.0, v19
	v_rcp_f32_e32 v18, v18
	v_rcp_f32_e32 v19, v19
	v_mul_f32_e32 v18, v30, v18
	v_mul_f32_e32 v19, v31, v19
	v_mul_f32_e32 v18, v22, v18
	v_mul_f32_e32 v19, v23, v19
	s_nop 0
	v_cvt_pk_bf16_f32 v18, v18, v19
	v_mul_f32_e32 v19, 0xbfb8aa3b, v32
	v_mul_f32_e32 v22, 0xbfb8aa3b, v33
	v_exp_f32_e32 v19, v19
	v_exp_f32_e32 v22, v22
	v_add_f32_e32 v19, 1.0, v19
	v_add_f32_e32 v22, 1.0, v22
	v_rcp_f32_e32 v19, v19
	v_rcp_f32_e32 v22, v22
	v_mul_f32_e32 v19, v32, v19
	v_mul_f32_e32 v22, v33, v22
	v_mul_f32_e32 v19, v24, v19
	v_mul_f32_e32 v22, v25, v22
	s_nop 0
	v_cvt_pk_bf16_f32 v19, v19, v22
	v_mul_f32_e32 v22, 0xbfb8aa3b, v26
	v_exp_f32_e32 v22, v22
	s_nop 0
	v_add_f32_e32 v22, 1.0, v22
	v_rcp_f32_e32 v22, v22
	s_nop 0
	v_mul_f32_e32 v22, v26, v22
	v_mul_f32_e32 v20, v20, v22
	v_mul_f32_e32 v22, 0xbfb8aa3b, v27
	v_exp_f32_e32 v22, v22
	s_nop 0
	v_add_f32_e32 v22, 1.0, v22
	v_rcp_f32_e32 v22, v22
	s_nop 0
	v_mul_f32_e32 v22, v27, v22
	v_mul_f32_e32 v21, v21, v22
	s_nop 0
	v_cvt_pk_bf16_f32 v20, v20, v21
	v_mul_f32_e32 v21, 0xbfb8aa3b, v28
	v_mul_f32_e32 v22, 0xbfb8aa3b, v29
	v_exp_f32_e32 v21, v21
	v_exp_f32_e32 v22, v22
	v_add_f32_e32 v21, 1.0, v21
	v_add_f32_e32 v22, 1.0, v22
	v_rcp_f32_e32 v21, v21
	v_rcp_f32_e32 v22, v22
	v_mul_f32_e32 v21, v28, v21
	v_mul_f32_e32 v22, v29, v22
	v_mul_f32_e32 v21, v34, v21
	v_mul_f32_e32 v22, v35, v22
	s_nop 0
	v_cvt_pk_bf16_f32 v21, v21, v22
	v_mad_i64_i32 v[22:23], s[18:19], v36, s74, v[134:135]
	v_lshl_add_u64 v[22:23], v[22:23], 0, v[136:137]
	global_store_dwordx4 v[22:23], v[18:21], off
	s_nop 1
	v_pk_fma_f32 v[18:19], v[2:3], v[158:159], v[72:73] op_sel_hi:[1,0,1]
	v_pk_fma_f32 v[2:3], v[0:1], v[158:159], v[70:71] op_sel_hi:[1,0,1]
	v_mul_f32_e32 v0, 0xbfb8aa3b, v14
	v_mul_f32_e32 v1, 0xbfb8aa3b, v15
	v_exp_f32_e32 v0, v0
	v_exp_f32_e32 v1, v1
	v_add_u32_e32 v20, 0xb0, v156
	v_add_f32_e32 v0, 1.0, v0
	v_add_f32_e32 v1, 1.0, v1
	v_rcp_f32_e32 v0, v0
	v_rcp_f32_e32 v1, v1
	v_mul_f32_e32 v0, v14, v0
	v_mul_f32_e32 v1, v15, v1
	v_mul_f32_e32 v0, v6, v0
	v_mul_f32_e32 v1, v7, v1
	s_nop 0
	v_cvt_pk_bf16_f32 v0, v0, v1
	v_mul_f32_e32 v1, 0xbfb8aa3b, v16
	v_mul_f32_e32 v6, 0xbfb8aa3b, v17
	v_exp_f32_e32 v1, v1
	v_exp_f32_e32 v6, v6
	v_add_f32_e32 v1, 1.0, v1
	v_add_f32_e32 v6, 1.0, v6
	v_rcp_f32_e32 v1, v1
	v_rcp_f32_e32 v6, v6
	v_mul_f32_e32 v1, v16, v1
	v_mul_f32_e32 v6, v17, v6
	v_mul_f32_e32 v1, v8, v1
	v_mul_f32_e32 v6, v9, v6
	s_nop 0
	v_cvt_pk_bf16_f32 v1, v1, v6
	v_mul_f32_e32 v6, 0xbfb8aa3b, v10
	v_exp_f32_e32 v6, v6
	s_nop 0
	v_add_f32_e32 v6, 1.0, v6
	v_rcp_f32_e32 v6, v6
	s_nop 0
	v_mul_f32_e32 v6, v10, v6
	v_mul_f32_e32 v2, v2, v6
	v_mul_f32_e32 v6, 0xbfb8aa3b, v11
	v_exp_f32_e32 v6, v6
	s_nop 0
	v_add_f32_e32 v6, 1.0, v6
	v_rcp_f32_e32 v6, v6
	s_nop 0
	v_mul_f32_e32 v6, v11, v6
	v_mul_f32_e32 v3, v3, v6
	s_nop 0
	v_cvt_pk_bf16_f32 v2, v2, v3
	v_mul_f32_e32 v3, 0xbfb8aa3b, v12
	v_mul_f32_e32 v6, 0xbfb8aa3b, v13
	v_exp_f32_e32 v3, v3
	v_exp_f32_e32 v6, v6
	v_add_f32_e32 v3, 1.0, v3
	v_add_f32_e32 v6, 1.0, v6
	v_rcp_f32_e32 v3, v3
	v_rcp_f32_e32 v6, v6
	v_mul_f32_e32 v3, v12, v3
	v_mul_f32_e32 v6, v13, v6
	v_mul_f32_e32 v3, v18, v3
	v_mul_f32_e32 v6, v19, v6
	s_nop 0
	v_cvt_pk_bf16_f32 v3, v3, v6
	v_mad_i64_i32 v[6:7], s[18:19], v20, s74, v[134:135]
	v_lshl_add_u64 v[6:7], v[6:7], 0, v[136:137]
	s_mov_b64 s[18:19], s[14:15]
	global_store_dwordx4 v[6:7], v[0:3], off
	s_cbranch_vccz .LBB0_2894
	s_waitcnt vmcnt(0)
	s_cmpk_gt_u32 s24, 0xff
	s_cbranch_scc1 .LBB0_2901
	s_barrier
